# speedup vs baseline: 1.0326x; 1.0076x over previous
.Lhf_idle:
	s_sub_i32 s6, 0x840, s61
	s_lshl_b32 s7, s6, 1
	s_cmp_gt_i32 s7, s42
	s_cbranch_scc1 .LBB0_145
	v_readlane_b32 s7, v254, 53
	s_add_i32 s64, s7, s61
	s_sub_i32 s64, s64, s6
	s_cmpk_lt_i32 s64, 0x840
	s_cbranch_scc0 .LBB0_145
	s_mov_b64 s[4:5], 0
	s_movk_i32 s11, 0x80
	s_branch .Lhf_tile
.Lhf_top:
	s_movk_i32 s11, 0
.Lhf_tile:
	s_mov_b32 s33, -1
	s_mul_hi_i32 s6, s64, 0x2e8ba2e9
	v_mbcnt_lo_u32_b32 v0, s33, 0
	v_mbcnt_hi_u32_b32 v0, s33, v0
	v_add_u32_e32 v132, s43, v0
	s_lshr_b32 s7, s6, 31
	v_bfe_i32 v3, v132, 27, 1
	v_lshlrev_b32_e32 v1, 4, v132
	v_lshrrev_b32_e32 v3, 22, v3
	v_add_u32_e32 v3, v1, v3
	v_and_b32_e32 v3, 0xfffffc00, v3
	v_ashrrev_i32_e32 v2, 31, v132
	v_sub_u32_e32 v3, v1, v3
	v_lshrrev_b32_e32 v2, 26, v2
	v_lshrrev_b32_e32 v4, 4, v3
	v_add_u32_e32 v2, v132, v2
	v_bitop3_b32 v4, v4, v3, 32 bitop3:0x6c
	v_ashrrev_i32_e32 v3, 31, v3
	v_ashrrev_i32_e32 v2, 6, v2
	v_lshrrev_b32_e32 v3, 26, v3
	v_lshlrev_b32_e32 v5, 3, v2
	v_add_u32_e32 v3, v4, v3
	v_and_b32_e32 v5, 0xffff0, v5
	v_ashrrev_i32_e32 v3, 6, v3
	v_add_u32_e32 v5, v3, v5
	v_mul_i32_i24_e32 v3, 64, v3
	v_lshlrev_b32_e32 v2, 5, v2
	v_sub_u32_e32 v3, v4, v3
	v_and_b32_e32 v2, 32, v2
	v_ashrrev_i16_sdwa v3, v226, sext(v3) dst_sel:DWORD dst_unused:UNUSED_PAD src0_sel:DWORD src1_sel:BYTE_0
	v_bfe_i32 v3, v3, 0, 16
	v_lshl_or_b32 v2, v5, 11, v2
	v_add_u32_e32 v1, 0x2000, v1
	v_add_lshl_u32 v128, v2, v3, 1
	v_ashrrev_i32_e32 v2, 31, v1
	s_ashr_i32 s6, s6, 6
	v_lshrrev_b32_e32 v2, 22, v2
	s_add_i32 s6, s6, s7
	v_add_u32_e32 v2, v1, v2
	s_mul_i32 s7, s6, 0x160
	v_ashrrev_i32_e32 v2, 10, v2
	s_sub_i32 s7, s64, s7
	v_mul_i32_i24_e32 v3, 0x400, v2
	s_sext_i32_i16 s8, s7
	v_sub_u32_e32 v1, v1, v3
	s_bfe_u32 s8, s8, 0x3001c
	v_lshrrev_b32_e32 v3, 4, v1
	s_add_i32 s8, s7, s8
	v_bitop3_b32 v1, v3, v1, 32 bitop3:0x6c
	s_sext_i32_i16 s9, s8
	s_and_b32 s8, s8, 0xfff8
	v_ashrrev_i32_e32 v4, 31, v1
	s_sub_i32 s7, s7, s8
	v_lshrrev_b32_e32 v4, 26, v4
	s_sext_i32_i16 s7, s7
	v_add_u32_e32 v4, v1, v4
	s_lshl_b32 s6, s6, 11
	s_lshl_b32 s7, s7, 8
	v_lshlrev_b32_e32 v3, 3, v2
	v_lshrrev_b32_e32 v5, 6, v4
	v_and_b32_e32 v4, 0xc0, v4
	s_add_i32 s8, s7, s6
	s_or_b32 s8, s8, s11
	s_lshl_b32 s6, s9, 5
	v_and_b32_e32 v3, 0xffff0, v3
	v_lshlrev_b32_e32 v2, 5, v2
	v_sub_u32_e32 v1, v1, v4
	s_and_b32 s6, s6, 0xffffff00
	v_ashrrev_i32_e32 v0, 6, v132
	v_add_u32_e32 v3, v5, v3
	v_and_b32_e32 v2, 32, v2
	v_ashrrev_i16_sdwa v1, v226, sext(v1) dst_sel:DWORD dst_unused:UNUSED_PAD src0_sel:DWORD src1_sel:BYTE_0
	s_or_b32 s28, s6, 0x80
	s_or_b32 s10, s8, 0x80
	v_readfirstlane_b32 s33, v0
	v_bfe_i32 v1, v1, 0, 16
	v_lshl_or_b32 v2, v3, 11, v2
	s_xor_b64 s[4:5], s[4:5], -1
	s_ashr_i32 s7, s6, 31
	s_ashr_i32 s9, s8, 31
	s_ashr_i32 s29, s28, 31
	s_ashr_i32 s11, s10, 31
	s_lshl_b32 s52, s33, 10
	s_andn2_b64 vcc, exec, s[4:5]
	v_add_lshl_u32 v130, v2, v1, 1
	s_cbranch_vccnz .Lhf_187
	s_lshl_b64 s[36:37], s[6:7], 12
	s_add_u32 s36, s67, s36
	s_addc_u32 s37, s60, s37
	v_mov_b32_e32 v1, v130
	v_mov_b32_e32 v2, v128
	s_add_i32 m0, s52, 0x10000
	v_readlane_b32 s38, v254, 12
	global_load_lds_dwordx4 v2, s[36:37]
	s_add_i32 m0, s52, 0x12000
	v_readlane_b32 s39, v254, 13
	global_load_lds_dwordx4 v1, s[36:37]
	s_lshl_b64 s[36:37], s[8:9], 12
	s_add_u32 s36, s38, s36
	s_addc_u32 s37, s39, s37
	v_mov_b32_e32 v1, v130
	v_mov_b32_e32 v2, v128
	s_mov_b32 m0, s52
	s_nop 0
	global_load_lds_dwordx4 v2, s[36:37]
	s_add_i32 m0, s52, 0x2000
	v_mov_b32_e32 v2, v128
	global_load_lds_dwordx4 v1, s[36:37]
	s_lshl_b64 s[36:37], s[28:29], 12
	s_add_u32 s36, s67, s36
	s_addc_u32 s37, s60, s37
	v_mov_b32_e32 v1, v130
	s_add_i32 m0, s52, 0x14000
	s_nop 0
	global_load_lds_dwordx4 v2, s[36:37]
	s_add_i32 m0, s52, 0x16000
	v_mov_b32_e32 v2, v128
	global_load_lds_dwordx4 v1, s[36:37]
	s_lshl_b64 s[36:37], s[10:11], 12
	s_add_u32 s36, s38, s36
	s_addc_u32 s37, s39, s37
	v_mov_b32_e32 v1, v130
	s_add_i32 m0, s52, 0x4000
	s_nop 0
	s_add_i32 m0, s52, 0x6000
	s_nop 0
	v_ashrrev_i32_e32 v1, 8, v132
	v_cmp_eq_u32_e32 vcc, 1, v1
	s_and_saveexec_b64 s[56:57], vcc
	s_cbranch_execnz .Lhf_188

.Lhf_186:
	s_waitcnt vmcnt(2)
	s_cbranch_execz .Lhf_190
	s_branch .Lhf_191

.Lhf_192:
	ds_read_b128 v[140:143], v129
	ds_read_b128 v[144:147], v129 offset:1024
	ds_read_b128 v[148:151], v129 offset:2048
	ds_read_b128 v[152:155], v129 offset:3072
	s_add_u32 s28, s56, s4
	v_mov_b32_e32 v196, v128
	v_mov_b32_e32 v188, v130
	s_addc_u32 s29, s57, s5
	ds_read_b128 v[156:159], v136
	ds_read_b128 v[160:163], v136 offset:1024
	ds_read_b128 v[164:167], v135
	ds_read_b128 v[168:171], v135 offset:1024
	ds_read_b128 v[172:175], v134
	ds_read_b128 v[176:179], v134 offset:1024
	ds_read_b128 v[180:183], v133
	ds_read_b128 v[184:187], v133 offset:1024
	s_add_i32 s40, s52, 0xc000
	v_lshl_add_u64 v[190:191], s[28:29], 0, v[196:197]
	v_mov_b32_e32 v189, v197
	v_lshl_add_u64 v[190:191], v[190:191], 0, s[44:45]
	s_mov_b32 m0, s40
	v_lshl_add_u64 v[188:189], s[28:29], 0, v[188:189]
	s_add_i32 s39, s52, 0xe000
	v_lshl_add_u64 v[188:189], v[188:189], 0, s[44:45]
	s_mov_b32 m0, s39
	s_nop 0
	s_waitcnt lgkmcnt(8)
	s_barrier
	s_waitcnt lgkmcnt(0)
	s_setprio 1
	s_waitcnt lgkmcnt(0)
	v_mfma_f32_16x16x32_bf16 v[124:127], v[140:143], v[156:159], v[124:127]
	v_mfma_f32_16x16x32_bf16 v[120:123], v[148:151], v[156:159], v[120:123]
	v_mfma_f32_16x16x32_bf16 v[116:119], v[140:143], v[164:167], v[116:119]
	v_mfma_f32_16x16x32_bf16 v[112:115], v[148:151], v[164:167], v[112:115]
	v_mfma_f32_16x16x32_bf16 v[108:111], v[140:143], v[172:175], v[108:111]
	v_mfma_f32_16x16x32_bf16 v[104:107], v[148:151], v[172:175], v[104:107]
	v_mfma_f32_16x16x32_bf16 v[100:103], v[140:143], v[180:183], v[100:103]
	v_mfma_f32_16x16x32_bf16 v[96:99], v[148:151], v[180:183], v[96:99]
	v_mfma_f32_16x16x32_bf16 v[124:127], v[144:147], v[160:163], v[124:127]
	v_mfma_f32_16x16x32_bf16 v[120:123], v[152:155], v[160:163], v[120:123]
	v_mfma_f32_16x16x32_bf16 v[116:119], v[144:147], v[168:171], v[116:119]
	v_mfma_f32_16x16x32_bf16 v[112:115], v[152:155], v[168:171], v[112:115]
	v_mfma_f32_16x16x32_bf16 v[108:111], v[144:147], v[176:179], v[108:111]
	v_mfma_f32_16x16x32_bf16 v[104:107], v[152:155], v[176:179], v[104:107]
	v_mfma_f32_16x16x32_bf16 v[100:103], v[144:147], v[184:187], v[100:103]
	v_mfma_f32_16x16x32_bf16 v[96:99], v[152:155], v[184:187], v[96:99]
	s_setprio 0
	s_barrier
	s_add_u32 s58, s56, s36
	v_mov_b32_e32 v196, v128
	v_mov_b32_e32 v210, v130
	s_addc_u32 s59, s57, s37
	ds_read_b128 v[188:191], v139
	ds_read_b128 v[192:195], v139 offset:1024
	ds_read_b128 v[202:205], v139 offset:2048
	ds_read_b128 v[206:209], v139 offset:3072
	v_mov_b32_e32 v211, v197
	v_lshl_add_u64 v[212:213], s[58:59], 0, v[196:197]
	v_lshl_add_u64 v[212:213], v[212:213], 0, s[46:47]
	s_add_i32 m0, s52, 0x10000
	v_lshl_add_u64 v[210:211], s[58:59], 0, v[210:211]
	global_load_lds_dwordx4 v[212:213], off
	v_lshl_add_u64 v[210:211], v[210:211], 0, s[46:47]
	s_add_i32 m0, s52, 0x12000
	s_nop 0
	global_load_lds_dwordx4 v[210:211], off
	s_barrier
	s_waitcnt lgkmcnt(0)
	s_setprio 1
	s_waitcnt lgkmcnt(0)
	v_mfma_f32_16x16x32_bf16 v[92:95], v[188:191], v[156:159], v[92:95]
	v_mfma_f32_16x16x32_bf16 v[88:91], v[202:205], v[156:159], v[88:91]
	v_mfma_f32_16x16x32_bf16 v[84:87], v[188:191], v[164:167], v[84:87]
	v_mfma_f32_16x16x32_bf16 v[80:83], v[202:205], v[164:167], v[80:83]
	v_mfma_f32_16x16x32_bf16 v[76:79], v[188:191], v[172:175], v[76:79]
	v_mfma_f32_16x16x32_bf16 v[72:75], v[202:205], v[172:175], v[72:75]
	v_mfma_f32_16x16x32_bf16 v[68:71], v[188:191], v[180:183], v[68:71]
	v_mfma_f32_16x16x32_bf16 v[64:67], v[202:205], v[180:183], v[64:67]
	v_mfma_f32_16x16x32_bf16 v[92:95], v[192:195], v[160:163], v[92:95]
	v_mfma_f32_16x16x32_bf16 v[88:91], v[206:209], v[160:163], v[88:91]
	v_mfma_f32_16x16x32_bf16 v[84:87], v[192:195], v[168:171], v[84:87]
	v_mfma_f32_16x16x32_bf16 v[80:83], v[206:209], v[168:171], v[80:83]
	v_mfma_f32_16x16x32_bf16 v[76:79], v[192:195], v[176:179], v[76:79]
	v_mfma_f32_16x16x32_bf16 v[72:75], v[206:209], v[176:179], v[72:75]
	v_mfma_f32_16x16x32_bf16 v[68:71], v[192:195], v[184:187], v[68:71]
	v_mfma_f32_16x16x32_bf16 v[64:67], v[206:209], v[184:187], v[64:67]
	s_setprio 0
	v_mov_b32_e32 v196, v128
	v_mov_b32_e32 v210, v130
	s_barrier
	v_mov_b32_e32 v211, v197
	v_lshl_add_u64 v[212:213], s[28:29], 0, v[196:197]
	s_mov_b32 m0, s52
	v_lshl_add_u64 v[212:213], v[212:213], 0, s[48:49]
	v_lshl_add_u64 v[210:211], s[28:29], 0, v[210:211]
	global_load_lds_dwordx4 v[212:213], off
	v_lshl_add_u64 v[210:211], v[210:211], 0, s[48:49]
	s_add_i32 m0, s52, 0x2000
	s_nop 0
	global_load_lds_dwordx4 v[210:211], off
	s_barrier
	s_waitcnt lgkmcnt(0)
	s_setprio 1
	s_waitcnt lgkmcnt(0)
	s_setprio 0
	s_barrier
	v_mov_b32_e32 v196, v128
	v_mov_b32_e32 v140, v130
	v_mov_b32_e32 v141, v197
	v_lshl_add_u64 v[142:143], s[58:59], 0, v[196:197]
	v_lshl_add_u64 v[142:143], v[142:143], 0, s[50:51]
	s_add_i32 m0, s52, 0x14000
	v_lshl_add_u64 v[140:141], s[58:59], 0, v[140:141]
	global_load_lds_dwordx4 v[142:143], off
	v_lshl_add_u64 v[140:141], v[140:141], 0, s[50:51]
	s_add_i32 m0, s52, 0x16000
	s_nop 0
	global_load_lds_dwordx4 v[140:141], off
	s_waitcnt vmcnt(6)
	s_barrier
	s_setprio 1
	s_setprio 0
	s_barrier
	ds_read_b128 v[140:143], v138
	ds_read_b128 v[144:147], v138 offset:1024
	ds_read_b128 v[148:151], v138 offset:2048
	ds_read_b128 v[152:155], v138 offset:3072
	v_mov_b32_e32 v196, v128
	v_mov_b32_e32 v188, v130
	ds_read_b128 v[156:159], v136 offset:32768
	ds_read_b128 v[160:163], v136 offset:33792
	ds_read_b128 v[164:167], v135 offset:32768
	ds_read_b128 v[168:171], v135 offset:33792
	ds_read_b128 v[172:175], v134 offset:32768
	ds_read_b128 v[176:179], v134 offset:33792
	ds_read_b128 v[180:183], v133 offset:32768
	ds_read_b128 v[184:187], v133 offset:33792
	v_mov_b32_e32 v189, v197
	v_lshl_add_u64 v[190:191], s[28:29], 0, v[196:197]
	v_lshl_add_u64 v[190:191], v[190:191], 0, s[54:55]
	s_add_i32 m0, s52, 0x4000
	v_lshl_add_u64 v[188:189], s[28:29], 0, v[188:189]
	v_lshl_add_u64 v[188:189], v[188:189], 0, s[54:55]
	s_add_i32 m0, s52, 0x6000
	s_nop 0
	s_waitcnt lgkmcnt(8)
	s_barrier
	s_waitcnt lgkmcnt(0)
	s_setprio 1
	s_waitcnt lgkmcnt(0)
	v_mfma_f32_16x16x32_bf16 v[124:127], v[140:143], v[156:159], v[124:127]
	v_mfma_f32_16x16x32_bf16 v[120:123], v[148:151], v[156:159], v[120:123]
	v_mfma_f32_16x16x32_bf16 v[116:119], v[140:143], v[164:167], v[116:119]
	v_mfma_f32_16x16x32_bf16 v[112:115], v[148:151], v[164:167], v[112:115]
	v_mfma_f32_16x16x32_bf16 v[108:111], v[140:143], v[172:175], v[108:111]
	v_mfma_f32_16x16x32_bf16 v[104:107], v[148:151], v[172:175], v[104:107]
	v_mfma_f32_16x16x32_bf16 v[100:103], v[140:143], v[180:183], v[100:103]
	v_mfma_f32_16x16x32_bf16 v[96:99], v[148:151], v[180:183], v[96:99]
	v_mfma_f32_16x16x32_bf16 v[124:127], v[144:147], v[160:163], v[124:127]
	v_mfma_f32_16x16x32_bf16 v[120:123], v[152:155], v[160:163], v[120:123]
	v_mfma_f32_16x16x32_bf16 v[116:119], v[144:147], v[168:171], v[116:119]
	v_mfma_f32_16x16x32_bf16 v[112:115], v[152:155], v[168:171], v[112:115]
	v_mfma_f32_16x16x32_bf16 v[108:111], v[144:147], v[176:179], v[108:111]
	v_mfma_f32_16x16x32_bf16 v[104:107], v[152:155], v[176:179], v[104:107]
	v_mfma_f32_16x16x32_bf16 v[100:103], v[144:147], v[184:187], v[100:103]
	v_mfma_f32_16x16x32_bf16 v[96:99], v[152:155], v[184:187], v[96:99]
	s_setprio 0
	s_barrier
	v_mov_b32_e32 v196, v128
	v_mov_b32_e32 v210, v130
	ds_read_b128 v[188:191], v137
	ds_read_b128 v[192:195], v137 offset:1024
	ds_read_b128 v[202:205], v137 offset:2048
	ds_read_b128 v[206:209], v137 offset:3072
	v_mov_b32_e32 v211, v197
	v_lshl_add_u64 v[212:213], s[58:59], 0, v[196:197]
	s_mov_b32 m0, s7
	v_lshl_add_u64 v[212:213], v[212:213], 0, s[68:69]
	v_lshl_add_u64 v[210:211], s[58:59], 0, v[210:211]
	global_load_lds_dwordx4 v[212:213], off
	v_lshl_add_u64 v[210:211], v[210:211], 0, s[68:69]
	s_mov_b32 m0, s53
	s_nop 0
	global_load_lds_dwordx4 v[210:211], off
	s_barrier
	s_waitcnt lgkmcnt(0)
	s_setprio 1
	s_waitcnt lgkmcnt(0)
	v_mfma_f32_16x16x32_bf16 v[92:95], v[188:191], v[156:159], v[92:95]
	v_mfma_f32_16x16x32_bf16 v[88:91], v[202:205], v[156:159], v[88:91]
	v_mfma_f32_16x16x32_bf16 v[84:87], v[188:191], v[164:167], v[84:87]
	v_mfma_f32_16x16x32_bf16 v[80:83], v[202:205], v[164:167], v[80:83]
	v_mfma_f32_16x16x32_bf16 v[76:79], v[188:191], v[172:175], v[76:79]
	v_mfma_f32_16x16x32_bf16 v[72:75], v[202:205], v[172:175], v[72:75]
	v_mfma_f32_16x16x32_bf16 v[68:71], v[188:191], v[180:183], v[68:71]
	v_mfma_f32_16x16x32_bf16 v[64:67], v[202:205], v[180:183], v[64:67]
	v_mfma_f32_16x16x32_bf16 v[92:95], v[192:195], v[160:163], v[92:95]
	v_mfma_f32_16x16x32_bf16 v[88:91], v[206:209], v[160:163], v[88:91]
	v_mfma_f32_16x16x32_bf16 v[84:87], v[192:195], v[168:171], v[84:87]
	v_mfma_f32_16x16x32_bf16 v[80:83], v[206:209], v[168:171], v[80:83]
	v_mfma_f32_16x16x32_bf16 v[76:79], v[192:195], v[176:179], v[76:79]
	v_mfma_f32_16x16x32_bf16 v[72:75], v[206:209], v[176:179], v[72:75]
	v_mfma_f32_16x16x32_bf16 v[68:71], v[192:195], v[184:187], v[68:71]
	v_mfma_f32_16x16x32_bf16 v[64:67], v[206:209], v[184:187], v[64:67]
	s_setprio 0
	v_mov_b32_e32 v196, v128
	v_mov_b32_e32 v210, v130
	s_barrier
	v_mov_b32_e32 v211, v197
	v_lshl_add_u64 v[212:213], s[28:29], 0, v[196:197]
	s_mov_b32 m0, s9
	v_lshl_add_u64 v[212:213], v[212:213], 0, s[70:71]
	v_lshl_add_u64 v[210:211], s[28:29], 0, v[210:211]
	global_load_lds_dwordx4 v[212:213], off
	v_lshl_add_u64 v[210:211], v[210:211], 0, s[70:71]
	s_mov_b32 m0, s33
	s_nop 0
	global_load_lds_dwordx4 v[210:211], off
	s_barrier
	s_waitcnt lgkmcnt(0)
	s_setprio 1
	s_waitcnt lgkmcnt(0)
	s_setprio 0
	s_barrier
	v_mov_b32_e32 v196, v128
	v_mov_b32_e32 v140, v130
	v_mov_b32_e32 v141, v197
	v_lshl_add_u64 v[142:143], s[58:59], 0, v[196:197]
	s_mov_b32 m0, s65
	v_lshl_add_u64 v[142:143], v[142:143], 0, s[72:73]
	v_lshl_add_u64 v[140:141], s[58:59], 0, v[140:141]
	global_load_lds_dwordx4 v[142:143], off
	v_lshl_add_u64 v[140:141], v[140:141], 0, s[72:73]
	s_mov_b32 m0, s66
	s_nop 0
	global_load_lds_dwordx4 v[140:141], off
	s_waitcnt vmcnt(6)
	s_barrier
	s_setprio 1
	s_setprio 0
	s_add_i32 s38, s38, 2
	s_add_u32 s56, s56, 0x100
	s_addc_u32 s57, s57, 0
	s_cmp_lt_u32 s38, 28
	s_barrier
	s_cbranch_scc1 .Lhf_192
	s_lshl_b64 s[4:5], s[10:11], 12
	v_readlane_b32 s10, v254, 12
	v_readlane_b32 s11, v254, 13
	s_add_u32 s4, s10, s4
	s_addc_u32 s5, s11, s5
	ds_read_b128 v[140:143], v129
	ds_read_b128 v[144:147], v129 offset:1024
	ds_read_b128 v[148:151], v129 offset:2048
	ds_read_b128 v[152:155], v129 offset:3072
	ds_read_b128 v[156:159], v136
	ds_read_b128 v[160:163], v136 offset:1024
	ds_read_b128 v[164:167], v135
	ds_read_b128 v[168:171], v135 offset:1024
	ds_read_b128 v[172:175], v134
	ds_read_b128 v[176:179], v134 offset:1024
	ds_read_b128 v[180:183], v133
	ds_read_b128 v[184:187], v133 offset:1024
	v_mov_b32_e32 v129, v197
	v_lshl_add_u64 v[128:129], s[4:5], 0, v[128:129]
	s_mov_b64 s[10:11], 0xf80
	s_mov_b32 m0, s40
	v_lshl_add_u64 v[128:129], v[128:129], 0, s[10:11]
	v_mov_b32_e32 v131, v197
	v_lshl_add_u64 v[128:129], s[4:5], 0, v[130:131]
	v_lshl_add_u64 v[128:129], v[128:129], 0, s[10:11]
	s_mov_b32 m0, s39
	s_nop 0
	s_barrier
	s_waitcnt lgkmcnt(0)
	s_setprio 1
	s_waitcnt lgkmcnt(0)
	v_mfma_f32_16x16x32_bf16 v[124:127], v[140:143], v[156:159], v[124:127]
	v_mfma_f32_16x16x32_bf16 v[116:119], v[140:143], v[164:167], v[116:119]
	v_mfma_f32_16x16x32_bf16 v[112:115], v[148:151], v[164:167], v[112:115]
	v_mfma_f32_16x16x32_bf16 v[108:111], v[140:143], v[172:175], v[108:111]
	v_mfma_f32_16x16x32_bf16 v[104:107], v[148:151], v[172:175], v[104:107]
	v_mfma_f32_16x16x32_bf16 v[100:103], v[140:143], v[180:183], v[100:103]
	v_mfma_f32_16x16x32_bf16 v[96:99], v[148:151], v[180:183], v[96:99]
	v_mfma_f32_16x16x32_bf16 v[124:127], v[144:147], v[160:163], v[124:127]
	v_mfma_f32_16x16x32_bf16 v[120:123], v[148:151], v[156:159], v[120:123]
	v_mfma_f32_16x16x32_bf16 v[116:119], v[144:147], v[168:171], v[116:119]
	v_mfma_f32_16x16x32_bf16 v[112:115], v[152:155], v[168:171], v[112:115]
	v_mfma_f32_16x16x32_bf16 v[108:111], v[144:147], v[176:179], v[108:111]
	v_mfma_f32_16x16x32_bf16 v[104:107], v[152:155], v[176:179], v[104:107]
	v_mfma_f32_16x16x32_bf16 v[100:103], v[144:147], v[184:187], v[100:103]
	v_mfma_f32_16x16x32_bf16 v[96:99], v[152:155], v[184:187], v[96:99]
	v_mfma_f32_16x16x32_bf16 v[128:131], v[152:155], v[160:163], v[120:123]
	s_setprio 0
	s_barrier
	s_nop 0
	ds_read_b128 v[120:123], v139
	ds_read_b128 v[188:191], v139 offset:1024
	ds_read_b128 v[192:195], v139 offset:2048
	ds_read_b128 v[202:205], v139 offset:3072
	s_barrier
	s_waitcnt lgkmcnt(0)
	s_setprio 1
	s_waitcnt lgkmcnt(0)
	v_mfma_f32_16x16x32_bf16 v[76:79], v[120:123], v[172:175], v[76:79]
	v_mfma_f32_16x16x32_bf16 v[68:71], v[120:123], v[180:183], v[68:71]
	v_mfma_f32_16x16x32_bf16 v[64:67], v[192:195], v[180:183], v[64:67]
	v_mfma_f32_16x16x32_bf16 v[92:95], v[120:123], v[156:159], v[92:95]
	v_mfma_f32_16x16x32_bf16 v[88:91], v[192:195], v[156:159], v[88:91]
	v_mfma_f32_16x16x32_bf16 v[84:87], v[120:123], v[164:167], v[84:87]
	v_mfma_f32_16x16x32_bf16 v[80:83], v[192:195], v[164:167], v[80:83]
	v_mfma_f32_16x16x32_bf16 v[76:79], v[188:191], v[176:179], v[76:79]
	v_mfma_f32_16x16x32_bf16 v[72:75], v[192:195], v[172:175], v[72:75]
	v_mfma_f32_16x16x32_bf16 v[68:71], v[188:191], v[184:187], v[68:71]
	v_mfma_f32_16x16x32_bf16 v[64:67], v[202:205], v[184:187], v[64:67]
	v_mfma_f32_16x16x32_bf16 v[206:209], v[188:191], v[160:163], v[92:95]
	v_mfma_f32_16x16x32_bf16 v[156:159], v[202:205], v[160:163], v[88:91]
	v_mfma_f32_16x16x32_bf16 v[160:163], v[188:191], v[168:171], v[84:87]
	v_mfma_f32_16x16x32_bf16 v[164:167], v[202:205], v[168:171], v[80:83]
	v_mfma_f32_16x16x32_bf16 v[168:171], v[202:205], v[176:179], v[72:75]
	s_setprio 0
	s_barrier
	s_nop 0
	s_waitcnt vmcnt(2)
	s_barrier
	s_waitcnt lgkmcnt(0)
	s_setprio 1
	s_waitcnt lgkmcnt(0)
	s_setprio 0
	s_setprio 1
	s_setprio 0
	s_barrier
	s_nop 0
	ds_read_b128 v[8:11], v138
	ds_read_b128 v[16:19], v138 offset:1024
	ds_read_b128 v[176:179], v138 offset:2048
	ds_read_b128 v[180:183], v138 offset:3072
	ds_read_b128 v[20:23], v136 offset:32768
	ds_read_b128 v[24:27], v136 offset:33792
	ds_read_b128 v[28:31], v135 offset:32768
	ds_read_b128 v[56:59], v135 offset:33792
	ds_read_b128 v[188:191], v134 offset:32768
	ds_read_b128 v[192:195], v134 offset:33792
	ds_read_b128 v[202:205], v133 offset:32768
	ds_read_b128 v[210:213], v133 offset:33792
	s_waitcnt vmcnt(0)
	s_barrier
	s_waitcnt lgkmcnt(0)
	s_setprio 1
	s_waitcnt lgkmcnt(0)
	v_mfma_f32_16x16x32_bf16 v[72:75], v[8:11], v[20:23], v[124:127]
	v_mfma_f32_16x16x32_bf16 v[120:123], v[16:19], v[24:27], v[72:75]
	v_mfma_f32_16x16x32_bf16 v[72:75], v[176:179], v[20:23], v[128:131]
	v_mfma_f32_16x16x32_bf16 v[124:127], v[180:183], v[24:27], v[72:75]
	v_mfma_f32_16x16x32_bf16 v[72:75], v[8:11], v[28:31], v[116:119]
	v_mfma_f32_16x16x32_bf16 v[116:119], v[16:19], v[56:59], v[72:75]
	v_mfma_f32_16x16x32_bf16 v[72:75], v[176:179], v[28:31], v[112:115]
	v_mfma_f32_16x16x32_bf16 v[112:115], v[180:183], v[56:59], v[72:75]
	v_mfma_f32_16x16x32_bf16 v[72:75], v[8:11], v[188:191], v[108:111]
	v_mfma_f32_16x16x32_bf16 v[88:91], v[16:19], v[192:195], v[72:75]
	v_mfma_f32_16x16x32_bf16 v[72:75], v[176:179], v[188:191], v[104:107]
	v_mfma_f32_16x16x32_bf16 v[92:95], v[180:183], v[192:195], v[72:75]
	v_mfma_f32_16x16x32_bf16 v[72:75], v[8:11], v[202:205], v[100:103]
	v_mfma_f32_16x16x32_bf16 v[84:87], v[16:19], v[210:213], v[72:75]
	v_mfma_f32_16x16x32_bf16 v[72:75], v[176:179], v[202:205], v[96:99]
	v_mfma_f32_16x16x32_bf16 v[80:83], v[180:183], v[210:213], v[72:75]
	s_setprio 0
	s_barrier
	ds_read_b128 v[128:131], v137
	ds_read_b128 v[214:217], v137 offset:1024
	ds_read_b128 v[218:221], v137 offset:2048
	ds_read_b128 v[222:225], v137 offset:3072
	s_waitcnt vmcnt(0)
	s_barrier
	s_waitcnt lgkmcnt(0)
	s_setprio 1
	s_waitcnt lgkmcnt(0)
	v_mfma_f32_16x16x32_bf16 v[72:75], v[128:131], v[20:23], v[206:209]
	v_mfma_f32_16x16x32_bf16 v[20:23], v[218:221], v[20:23], v[156:159]
	v_mfma_f32_16x16x32_bf16 v[108:111], v[222:225], v[24:27], v[20:23]
	v_mfma_f32_16x16x32_bf16 v[20:23], v[128:131], v[28:31], v[160:163]
	v_mfma_f32_16x16x32_bf16 v[100:103], v[214:217], v[56:59], v[20:23]
	v_mfma_f32_16x16x32_bf16 v[20:23], v[218:221], v[28:31], v[164:167]
	v_mfma_f32_16x16x32_bf16 v[96:99], v[222:225], v[56:59], v[20:23]
	v_mfma_f32_16x16x32_bf16 v[20:23], v[128:131], v[188:191], v[76:79]
	v_mfma_f32_16x16x32_bf16 v[104:107], v[214:217], v[24:27], v[72:75]
	v_mfma_f32_16x16x32_bf16 v[72:75], v[214:217], v[192:195], v[20:23]
	v_mfma_f32_16x16x32_bf16 v[20:23], v[218:221], v[188:191], v[168:171]
	v_mfma_f32_16x16x32_bf16 v[76:79], v[222:225], v[192:195], v[20:23]
	v_mfma_f32_16x16x32_bf16 v[20:23], v[128:131], v[202:205], v[68:71]
	v_mfma_f32_16x16x32_bf16 v[68:71], v[214:217], v[210:213], v[20:23]
	v_mfma_f32_16x16x32_bf16 v[20:23], v[218:221], v[202:205], v[64:67]
	v_mfma_f32_16x16x32_bf16 v[64:67], v[222:225], v[210:213], v[20:23]
	s_setprio 0
	s_barrier
	s_barrier
	s_waitcnt lgkmcnt(0)
	s_setprio 1
	s_waitcnt lgkmcnt(0)
	s_setprio 0
	s_setprio 1
	s_setprio 0
	s_movk_i32 s4, 0x100
	v_cmp_gt_u32_e32 vcc, s4, v132
	s_barrier
	s_and_saveexec_b64 s[4:5], vcc
	s_cbranch_execz .Lhf_195
	s_barrier
.Lhf_195:
	s_or_b64 exec, exec, s[4:5]
	v_readlane_b32 s40, v254, 59
	s_mov_b32 s7, -1
	v_mbcnt_lo_u32_b32 v128, s7, 0
	v_mbcnt_hi_u32_b32 v128, s7, v128
	v_add_u32_e32 v129, s43, v128
	v_ashrrev_i32_e32 v128, 2, v129
	v_and_b32_e32 v128, 0xffffffc0, v128
	v_and_or_b32 v130, v129, 15, s8
	v_add_u32_e32 v128, v130, v128
	v_lshrrev_b32_e32 v130, 1, v129
	v_and_b32_e32 v130, 0x60, v130
	v_or_b32_e32 v130, s6, v130
	v_lshrrev_b32_e32 v131, 2, v129
	v_ashrrev_i32_e32 v130, 1, v130
	v_and_or_b32 v134, v131, 8, v130
	v_mul_f32_e32 v130, 0xbfb8aa3b, v120
	v_mul_f32_e32 v131, 0xbfb8aa3b, v121
	v_exp_f32_e32 v130, v130
	v_exp_f32_e32 v131, v131
	v_and_b32_e32 v129, 16, v129
	v_or_b32_e32 v135, v128, v129
	v_add_f32_e32 v130, 1.0, v130
	v_add_f32_e32 v131, 1.0, v131
	v_rcp_f32_e32 v130, v130
	v_rcp_f32_e32 v131, v131
	s_movk_i32 s8, 0x2c00
	v_pk_mul_f32 v[120:121], v[120:121], v[130:131]
	s_nop 0
	v_pk_mul_f32 v[120:121], v[124:125], v[120:121]
	s_nop 0
	v_cvt_pk_bf16_f32 v130, v120, v121
	v_mul_f32_e32 v120, 0xbfb8aa3b, v116
	v_mul_f32_e32 v121, 0xbfb8aa3b, v117
	v_exp_f32_e32 v120, v120
	v_exp_f32_e32 v121, v121
	v_add_f32_e32 v120, 1.0, v120
	v_add_f32_e32 v121, 1.0, v121
	v_rcp_f32_e32 v120, v120
	v_rcp_f32_e32 v121, v121
	s_nop 0
	v_pk_mul_f32 v[116:117], v[116:117], v[120:121]
	s_nop 0
	v_pk_mul_f32 v[112:113], v[112:113], v[116:117]
	s_nop 0
	v_cvt_pk_bf16_f32 v132, v112, v113
	v_mul_f32_e32 v112, 0xbfb8aa3b, v122
	v_mul_f32_e32 v113, 0xbfb8aa3b, v123
	v_exp_f32_e32 v112, v112
	v_exp_f32_e32 v113, v113
	v_permlane16_swap_b32_e32 v130, v132
	v_add_f32_e32 v112, 1.0, v112
	v_add_f32_e32 v113, 1.0, v113
	v_rcp_f32_e32 v112, v112
	v_rcp_f32_e32 v113, v113
	s_nop 0
	v_pk_mul_f32 v[112:113], v[122:123], v[112:113]
	s_nop 0
	v_pk_mul_f32 v[112:113], v[126:127], v[112:113]
	s_nop 0
	v_cvt_pk_bf16_f32 v131, v112, v113
	v_mul_f32_e32 v112, 0xbfb8aa3b, v118
	v_mul_f32_e32 v113, 0xbfb8aa3b, v119
	v_exp_f32_e32 v112, v112
	v_exp_f32_e32 v113, v113
	v_add_f32_e32 v112, 1.0, v112
	v_add_f32_e32 v113, 1.0, v113
	v_rcp_f32_e32 v112, v112
	v_rcp_f32_e32 v113, v113
	s_nop 0
	v_pk_mul_f32 v[112:113], v[118:119], v[112:113]
	s_nop 0
	v_pk_mul_f32 v[112:113], v[114:115], v[112:113]
	s_nop 0
	v_cvt_pk_bf16_f32 v133, v112, v113
	v_mov_b64_e32 v[112:113], s[80:81]
	v_mad_i64_i32 v[116:117], s[6:7], v135, s8, v[112:113]
	v_ashrrev_i32_e32 v135, 31, v134
	v_lshlrev_b64 v[114:115], 1, v[134:135]
	v_lshl_add_u64 v[120:121], v[116:117], 0, v[114:115]
	v_mul_f32_e32 v116, 0xbfb8aa3b, v104
	v_mul_f32_e32 v117, 0xbfb8aa3b, v105
	v_exp_f32_e32 v116, v116
	v_exp_f32_e32 v117, v117
	v_permlane16_swap_b32_e32 v131, v133
	v_add_f32_e32 v116, 1.0, v116
	v_add_f32_e32 v117, 1.0, v117
	v_rcp_f32_e32 v116, v116
	v_rcp_f32_e32 v117, v117
	global_store_dwordx4 v[120:121], v[130:133], off
	v_pk_mul_f32 v[104:105], v[104:105], v[116:117]
	s_nop 0
	v_pk_mul_f32 v[104:105], v[108:109], v[104:105]
	s_nop 0
	v_cvt_pk_bf16_f32 v116, v104, v105
	v_mul_f32_e32 v104, 0xbfb8aa3b, v100
	v_mul_f32_e32 v105, 0xbfb8aa3b, v101
	v_exp_f32_e32 v104, v104
	v_exp_f32_e32 v105, v105
	v_add_f32_e32 v104, 1.0, v104
	v_add_f32_e32 v105, 1.0, v105
	v_rcp_f32_e32 v104, v104
	v_rcp_f32_e32 v105, v105
	s_nop 0
	v_pk_mul_f32 v[100:101], v[100:101], v[104:105]
	s_nop 0
	v_pk_mul_f32 v[96:97], v[96:97], v[100:101]
	s_nop 0
	v_cvt_pk_bf16_f32 v118, v96, v97
	v_mul_f32_e32 v96, 0xbfb8aa3b, v106
	v_mul_f32_e32 v97, 0xbfb8aa3b, v107
	v_exp_f32_e32 v96, v96
	v_exp_f32_e32 v97, v97
	v_permlane16_swap_b32_e32 v116, v118
	v_add_f32_e32 v96, 1.0, v96
	v_add_f32_e32 v97, 1.0, v97
	v_rcp_f32_e32 v96, v96
	v_rcp_f32_e32 v97, v97
	s_nop 0
	v_pk_mul_f32 v[96:97], v[106:107], v[96:97]
	s_nop 0
	v_pk_mul_f32 v[96:97], v[110:111], v[96:97]
	s_nop 0
	v_cvt_pk_bf16_f32 v117, v96, v97
	v_mul_f32_e32 v96, 0xbfb8aa3b, v102
	v_mul_f32_e32 v97, 0xbfb8aa3b, v103
	v_exp_f32_e32 v96, v96
	v_exp_f32_e32 v97, v97
	v_add_f32_e32 v96, 1.0, v96
	v_add_f32_e32 v97, 1.0, v97
	v_rcp_f32_e32 v96, v96
	v_rcp_f32_e32 v97, v97
	s_nop 0
	v_pk_mul_f32 v[96:97], v[102:103], v[96:97]
	s_nop 0
	v_pk_mul_f32 v[96:97], v[98:99], v[96:97]
	s_nop 0
	v_cvt_pk_bf16_f32 v119, v96, v97
	s_nop 1
	v_permlane16_swap_b32_e32 v117, v119
	global_store_dwordx4 v[120:121], v[116:119], off offset:128
	v_mul_f32_e32 v98, 0xbfb8aa3b, v88
	v_mul_f32_e32 v99, 0xbfb8aa3b, v89
	v_exp_f32_e32 v98, v98
	v_exp_f32_e32 v99, v99
	v_or_b32_e32 v96, 32, v129
	v_or_b32_e32 v97, v128, v96
	v_add_f32_e32 v98, 1.0, v98
	v_add_f32_e32 v99, 1.0, v99
	v_rcp_f32_e32 v98, v98
	v_rcp_f32_e32 v99, v99
	s_nop 0
	v_pk_mul_f32 v[88:89], v[88:89], v[98:99]
	s_nop 0
	v_pk_mul_f32 v[88:89], v[92:93], v[88:89]
	s_nop 0
	v_cvt_pk_bf16_f32 v98, v88, v89
	v_mul_f32_e32 v88, 0xbfb8aa3b, v84
	v_mul_f32_e32 v89, 0xbfb8aa3b, v85
	v_exp_f32_e32 v88, v88
	v_exp_f32_e32 v89, v89
	v_add_f32_e32 v88, 1.0, v88
	v_add_f32_e32 v89, 1.0, v89
	v_rcp_f32_e32 v88, v88
	v_rcp_f32_e32 v89, v89
	s_nop 0
	v_pk_mul_f32 v[84:85], v[84:85], v[88:89]
	s_nop 0
	v_pk_mul_f32 v[80:81], v[80:81], v[84:85]
	s_nop 0
	v_cvt_pk_bf16_f32 v100, v80, v81
	v_mul_f32_e32 v80, 0xbfb8aa3b, v90
	v_mul_f32_e32 v81, 0xbfb8aa3b, v91
	v_exp_f32_e32 v80, v80
	v_exp_f32_e32 v81, v81
	v_permlane16_swap_b32_e32 v98, v100
	v_add_f32_e32 v80, 1.0, v80
	v_add_f32_e32 v81, 1.0, v81
	v_rcp_f32_e32 v80, v80
	v_rcp_f32_e32 v81, v81
	s_nop 0
	v_pk_mul_f32 v[80:81], v[90:91], v[80:81]
	s_nop 0
	v_pk_mul_f32 v[80:81], v[94:95], v[80:81]
	s_nop 0
	v_cvt_pk_bf16_f32 v99, v80, v81
	v_mul_f32_e32 v80, 0xbfb8aa3b, v86
	v_mul_f32_e32 v81, 0xbfb8aa3b, v87
	v_exp_f32_e32 v80, v80
	v_exp_f32_e32 v81, v81
	v_add_f32_e32 v80, 1.0, v80
	v_add_f32_e32 v81, 1.0, v81
	v_rcp_f32_e32 v80, v80
	v_rcp_f32_e32 v81, v81
	s_nop 0
	v_pk_mul_f32 v[80:81], v[86:87], v[80:81]
	s_nop 0
	v_pk_mul_f32 v[80:81], v[82:83], v[80:81]
	s_nop 0
	v_cvt_pk_bf16_f32 v101, v80, v81
	v_mad_i64_i32 v[80:81], s[6:7], v97, s8, v[112:113]
	v_lshl_add_u64 v[84:85], v[80:81], 0, v[114:115]
	v_mul_f32_e32 v80, 0xbfb8aa3b, v72
	v_mul_f32_e32 v81, 0xbfb8aa3b, v73
	v_exp_f32_e32 v80, v80
	v_exp_f32_e32 v81, v81
	v_permlane16_swap_b32_e32 v99, v101
	v_add_f32_e32 v80, 1.0, v80
	v_add_f32_e32 v81, 1.0, v81
	v_rcp_f32_e32 v80, v80
	v_rcp_f32_e32 v81, v81
	global_store_dwordx4 v[84:85], v[98:101], off
	v_pk_mul_f32 v[72:73], v[72:73], v[80:81]
	s_nop 0
	v_pk_mul_f32 v[72:73], v[76:77], v[72:73]
	s_nop 0
	v_cvt_pk_bf16_f32 v80, v72, v73
	v_mul_f32_e32 v72, 0xbfb8aa3b, v68
	v_mul_f32_e32 v73, 0xbfb8aa3b, v69
	v_exp_f32_e32 v72, v72
	v_exp_f32_e32 v73, v73
	v_add_f32_e32 v72, 1.0, v72
	v_add_f32_e32 v73, 1.0, v73
	v_rcp_f32_e32 v72, v72
	v_rcp_f32_e32 v73, v73
	s_nop 0
	v_pk_mul_f32 v[68:69], v[68:69], v[72:73]
	s_nop 0
	v_pk_mul_f32 v[64:65], v[64:65], v[68:69]
	v_add_u32_e32 v68, 0x80, v128
	v_cvt_pk_bf16_f32 v82, v64, v65
	v_mul_f32_e32 v64, 0xbfb8aa3b, v74
	v_mul_f32_e32 v65, 0xbfb8aa3b, v75
	v_exp_f32_e32 v64, v64
	v_exp_f32_e32 v65, v65
	v_permlane16_swap_b32_e32 v80, v82
	v_add_f32_e32 v64, 1.0, v64
	v_add_f32_e32 v65, 1.0, v65
	v_rcp_f32_e32 v64, v64
	v_rcp_f32_e32 v65, v65
	s_nop 0
	v_pk_mul_f32 v[64:65], v[74:75], v[64:65]
	s_nop 0
	v_pk_mul_f32 v[64:65], v[78:79], v[64:65]
	s_nop 0
	v_cvt_pk_bf16_f32 v81, v64, v65
	v_mul_f32_e32 v64, 0xbfb8aa3b, v70
	v_mul_f32_e32 v65, 0xbfb8aa3b, v71
	v_exp_f32_e32 v64, v64
	v_exp_f32_e32 v65, v65
	v_add_f32_e32 v64, 1.0, v64
	v_add_f32_e32 v65, 1.0, v65
	v_rcp_f32_e32 v64, v64
	v_rcp_f32_e32 v65, v65
	s_nop 0
	v_pk_mul_f32 v[64:65], v[70:71], v[64:65]
	s_nop 0
	v_pk_mul_f32 v[64:65], v[66:67], v[64:65]
	s_nop 0
	v_cvt_pk_bf16_f32 v83, v64, v65
	s_nop 1
	v_permlane16_swap_b32_e32 v81, v83
	global_store_dwordx4 v[84:85], v[80:83], off offset:128
	s_mov_b64 s[4:5], 0
	s_branch .LBB0_145

.LBB0_182:
	s_andn2_b64 vcc, exec, s[6:7]
	s_cbranch_vccnz .Lhf_idle
	s_sub_i32 s6, 0x840, s61
	s_lshl_b32 s6, s6, 1
	s_cmp_le_i32 s6, s42
	s_cbranch_scc1 .Lhf_top
	s_mov_b32 s33, -1
	s_mul_hi_i32 s6, s64, 0x2e8ba2e9
	v_mbcnt_lo_u32_b32 v0, s33, 0
	v_mbcnt_hi_u32_b32 v0, s33, v0
	v_add_u32_e32 v132, s43, v0
	s_lshr_b32 s7, s6, 31
	v_bfe_i32 v3, v132, 27, 1
	v_lshlrev_b32_e32 v1, 4, v132
	v_lshrrev_b32_e32 v3, 22, v3
	v_add_u32_e32 v3, v1, v3
	v_and_b32_e32 v3, 0xfffffc00, v3
	v_ashrrev_i32_e32 v2, 31, v132
	v_sub_u32_e32 v3, v1, v3
	v_lshrrev_b32_e32 v2, 26, v2
	v_lshrrev_b32_e32 v4, 4, v3
	v_add_u32_e32 v2, v132, v2
	v_bitop3_b32 v4, v4, v3, 32 bitop3:0x6c
	v_ashrrev_i32_e32 v3, 31, v3
	v_ashrrev_i32_e32 v2, 6, v2
	v_lshrrev_b32_e32 v3, 26, v3
	v_lshlrev_b32_e32 v5, 3, v2
	v_add_u32_e32 v3, v4, v3
	v_and_b32_e32 v5, 0xffff0, v5
	v_ashrrev_i32_e32 v3, 6, v3
	v_add_u32_e32 v5, v3, v5
	v_mul_i32_i24_e32 v3, 64, v3
	v_lshlrev_b32_e32 v2, 5, v2
	v_sub_u32_e32 v3, v4, v3
	v_and_b32_e32 v2, 32, v2
	v_ashrrev_i16_sdwa v3, v226, sext(v3) dst_sel:DWORD dst_unused:UNUSED_PAD src0_sel:DWORD src1_sel:BYTE_0
	v_bfe_i32 v3, v3, 0, 16
	v_lshl_or_b32 v2, v5, 11, v2
	v_add_u32_e32 v1, 0x2000, v1
	v_add_lshl_u32 v128, v2, v3, 1
	v_ashrrev_i32_e32 v2, 31, v1
	s_ashr_i32 s6, s6, 6
	v_lshrrev_b32_e32 v2, 22, v2
	s_add_i32 s6, s6, s7
	v_add_u32_e32 v2, v1, v2
	s_mul_i32 s7, s6, 0x160
	v_ashrrev_i32_e32 v2, 10, v2
	s_sub_i32 s7, s64, s7
	v_mul_i32_i24_e32 v3, 0x400, v2
	s_sext_i32_i16 s8, s7
	v_sub_u32_e32 v1, v1, v3
	s_bfe_u32 s8, s8, 0x3001c
	v_lshrrev_b32_e32 v3, 4, v1
	s_add_i32 s8, s7, s8
	v_bitop3_b32 v1, v3, v1, 32 bitop3:0x6c
	s_sext_i32_i16 s9, s8
	s_and_b32 s8, s8, 0xfff8
	v_ashrrev_i32_e32 v4, 31, v1
	s_sub_i32 s7, s7, s8
	v_lshrrev_b32_e32 v4, 26, v4
	s_sext_i32_i16 s7, s7
	v_add_u32_e32 v4, v1, v4
	s_lshl_b32 s6, s6, 11
	s_lshl_b32 s7, s7, 8
	v_lshlrev_b32_e32 v3, 3, v2
	v_lshrrev_b32_e32 v5, 6, v4
	v_and_b32_e32 v4, 0xc0, v4
	s_add_i32 s8, s7, s6
	s_lshl_b32 s6, s9, 5
	v_and_b32_e32 v3, 0xffff0, v3
	v_lshlrev_b32_e32 v2, 5, v2
	v_sub_u32_e32 v1, v1, v4
	s_and_b32 s6, s6, 0xffffff00
	v_ashrrev_i32_e32 v0, 6, v132
	v_add_u32_e32 v3, v5, v3
	v_and_b32_e32 v2, 32, v2
	v_ashrrev_i16_sdwa v1, v226, sext(v1) dst_sel:DWORD dst_unused:UNUSED_PAD src0_sel:DWORD src1_sel:BYTE_0
	s_or_b32 s28, s6, 0x80
	s_or_b32 s10, s8, 0x80
	v_readfirstlane_b32 s33, v0
	v_bfe_i32 v1, v1, 0, 16
	v_lshl_or_b32 v2, v3, 11, v2
	s_xor_b64 s[4:5], s[4:5], -1
	s_ashr_i32 s7, s6, 31
	s_ashr_i32 s9, s8, 31
	s_ashr_i32 s29, s28, 31
	s_ashr_i32 s11, s10, 31
	s_lshl_b32 s52, s33, 10
	s_andn2_b64 vcc, exec, s[4:5]
	v_add_lshl_u32 v130, v2, v1, 1
	s_cbranch_vccnz .LBB0_187
	s_lshl_b64 s[36:37], s[6:7], 12
	s_add_u32 s36, s67, s36
	s_addc_u32 s37, s60, s37
	v_mov_b32_e32 v1, v130
	v_mov_b32_e32 v2, v128
	s_add_i32 m0, s52, 0x10000
	v_readlane_b32 s38, v254, 12
	global_load_lds_dwordx4 v2, s[36:37]
	s_add_i32 m0, s52, 0x12000
	v_readlane_b32 s39, v254, 13
	global_load_lds_dwordx4 v1, s[36:37]
	s_lshl_b64 s[36:37], s[8:9], 12
	s_add_u32 s36, s38, s36
	s_addc_u32 s37, s39, s37
	v_mov_b32_e32 v1, v130
	v_mov_b32_e32 v2, v128
	s_mov_b32 m0, s52
	s_nop 0
	global_load_lds_dwordx4 v2, s[36:37]
	s_add_i32 m0, s52, 0x2000
	v_mov_b32_e32 v2, v128
	global_load_lds_dwordx4 v1, s[36:37]
	s_lshl_b64 s[36:37], s[28:29], 12
	s_add_u32 s36, s67, s36
	s_addc_u32 s37, s60, s37
	v_mov_b32_e32 v1, v130
	s_add_i32 m0, s52, 0x14000
	s_nop 0
	global_load_lds_dwordx4 v2, s[36:37]
	s_add_i32 m0, s52, 0x16000
	v_mov_b32_e32 v2, v128
	global_load_lds_dwordx4 v1, s[36:37]
	s_lshl_b64 s[36:37], s[10:11], 12
	s_add_u32 s36, s38, s36
	s_addc_u32 s37, s39, s37
	v_mov_b32_e32 v1, v130
	s_add_i32 m0, s52, 0x4000
	s_nop 0
	global_load_lds_dwordx4 v2, s[36:37]
	s_add_i32 m0, s52, 0x6000
	s_nop 0
	global_load_lds_dwordx4 v1, s[36:37]
	v_ashrrev_i32_e32 v1, 8, v132
	v_cmp_eq_u32_e32 vcc, 1, v1
	s_and_saveexec_b64 s[56:57], vcc
	s_cbranch_execnz .LBB0_188

.Lh1_idle:
	s_sub_i32 s6, 0x180, s55
	s_lshl_b32 s7, s6, 1
	s_cmp_gt_i32 s7, s42
	s_cbranch_scc1 .LBB0_213
	v_readlane_b32 s7, v254, 53
	s_add_i32 s33, s7, s55
	s_sub_i32 s33, s33, s6
	s_cmpk_lt_i32 s33, 0x180
	s_cbranch_scc0 .LBB0_213
	s_movk_i32 s59, 0x80
	s_branch .Lh1_tile
.Lh1_top:
	s_movk_i32 s59, 0
.Lh1_tile:
	s_mov_b32 s28, -1
	s_ashr_i32 s6, s33, 31
	v_mbcnt_lo_u32_b32 v0, s28, 0
	v_mbcnt_hi_u32_b32 v0, s28, v0
	v_add_u32_e32 v132, s43, v0
	s_lshr_b32 s6, s6, 26
	v_bfe_i32 v4, v132, 27, 1
	v_lshlrev_b32_e32 v2, 4, v132
	v_lshrrev_b32_e32 v4, 22, v4
	v_add_u32_e32 v4, v2, v4
	v_and_b32_e32 v4, 0xfffffc00, v4
	v_ashrrev_i32_e32 v3, 31, v132
	v_sub_u32_e32 v4, v2, v4
	v_lshrrev_b32_e32 v3, 26, v3
	v_lshrrev_b32_e32 v5, 4, v4
	v_add_u32_e32 v3, v132, v3
	v_bitop3_b32 v5, v5, v4, 32 bitop3:0x6c
	v_ashrrev_i32_e32 v4, 31, v4
	v_ashrrev_i32_e32 v3, 6, v3
	v_lshrrev_b32_e32 v4, 26, v4
	v_lshlrev_b32_e32 v6, 3, v3
	v_add_u32_e32 v4, v5, v4
	v_and_b32_e32 v6, 0xffff0, v6
	v_ashrrev_i32_e32 v4, 6, v4
	v_add_u32_e32 v6, v4, v6
	v_mul_i32_i24_e32 v4, 64, v4
	v_lshlrev_b32_e32 v3, 5, v3
	v_sub_u32_e32 v4, v5, v4
	v_and_b32_e32 v3, 32, v3
	v_ashrrev_i16_sdwa v4, v226, sext(v4) dst_sel:DWORD dst_unused:UNUSED_PAD src0_sel:DWORD src1_sel:BYTE_0
	v_bfe_i32 v4, v4, 0, 16
	v_lshl_or_b32 v3, v6, 11, v3
	v_add_u32_e32 v2, 0x2000, v2
	v_add_lshl_u32 v128, v3, v4, 1
	v_ashrrev_i32_e32 v3, 31, v2
	s_add_i32 s6, s33, s6
	v_lshrrev_b32_e32 v3, 22, v3
	s_ashr_i32 s7, s6, 6
	s_and_b32 s6, s6, 0xffc0
	v_add_u32_e32 v3, v2, v3
	s_sub_i32 s6, s33, s6
	v_ashrrev_i32_e32 v3, 10, v3
	s_lshl_b32 s52, s7, 3
	s_bfe_i32 s7, s6, 0x80000
	v_mul_i32_i24_e32 v4, 0x400, v3
	s_bfe_u32 s7, s7, 0x3000c
	v_sub_u32_e32 v2, v2, v4
	s_add_i32 s7, s6, s7
	v_lshrrev_b32_e32 v4, 4, v2
	s_bfe_i32 s8, s7, 0x80000
	s_and_b32 s7, s7, 0xf8
	v_bitop3_b32 v2, v4, v2, 32 bitop3:0x6c
	s_sub_i32 s6, s6, s7
	v_ashrrev_i32_e32 v5, 31, v2
	s_sext_i32_i16 s8, s8
	s_sext_i32_i8 s6, s6
	v_lshrrev_b32_e32 v5, 26, v5
	s_add_i32 s52, s52, s6
	s_lshl_b32 s6, s8, 5
	v_add_u32_e32 v5, v2, v5
	s_lshl_b32 s10, s52, 8
	s_or_b32 s10, s10, s59
	s_and_b32 s6, s6, 0xffffff00
	v_ashrrev_i32_e32 v1, 6, v132
	v_lshlrev_b32_e32 v4, 3, v3
	v_lshrrev_b32_e32 v6, 6, v5
	v_and_b32_e32 v5, 0xc0, v5
	s_ashr_i32 s7, s6, 31
	s_or_b32 s8, s6, 0x80
	s_or_b32 s58, s10, 0x80
	v_readfirstlane_b32 s28, v1
	v_and_b32_e32 v4, 0xffff0, v4
	v_lshlrev_b32_e32 v3, 5, v3
	v_sub_u32_e32 v2, v2, v5
	s_ashr_i32 s11, s10, 31
	s_ashr_i32 s9, s8, 31
	s_ashr_i32 s59, s58, 31
	s_lshl_b32 s53, s28, 10
	v_add_u32_e32 v4, v6, v4
	v_and_b32_e32 v3, 32, v3
	v_ashrrev_i16_sdwa v2, v226, sext(v2) dst_sel:DWORD dst_unused:UNUSED_PAD src0_sel:DWORD src1_sel:BYTE_0
	s_lshl_b64 s[28:29], s[6:7], 12
	v_bfe_i32 v2, v2, 0, 16
	v_lshl_or_b32 v3, v4, 11, v3
	s_add_u32 s64, s34, s28
	v_add_lshl_u32 v130, v3, v2, 1
	s_addc_u32 s65, s54, s29
	s_add_i32 s68, s53, 0x10000
	s_add_i32 s69, s53, 0x12000
	s_lshl_b64 s[56:57], s[10:11], 12
	v_readlane_b32 s33, v254, 14
	v_mov_b32_e32 v2, v128
	v_mov_b32_e32 v3, v130
	s_mov_b32 m0, s68
	s_add_u32 s62, s33, s56
	v_readlane_b32 s38, v254, 15
	s_addc_u32 s63, s38, s57
	global_load_lds_dwordx4 v2, s[64:65]
	s_mov_b32 m0, s69
	s_add_i32 s11, s53, 0x2000
	s_lshl_b64 s[36:37], s[8:9], 12
	global_load_lds_dwordx4 v3, s[64:65]
	v_mov_b32_e32 v2, v128
	v_mov_b32_e32 v3, v130
	s_mov_b32 m0, s53
	s_add_u32 s60, s34, s36
	s_addc_u32 s61, s54, s37
	global_load_lds_dwordx4 v2, s[62:63]
	s_mov_b32 m0, s11
	s_add_i32 s9, s53, 0x14000
	s_add_i32 s70, s53, 0x16000
	s_lshl_b64 s[36:37], s[58:59], 12
	global_load_lds_dwordx4 v3, s[62:63]
	v_mov_b32_e32 v2, v128
	v_mov_b32_e32 v3, v130
	s_mov_b32 m0, s9
	s_add_u32 s58, s33, s36
	s_addc_u32 s59, s38, s37
	global_load_lds_dwordx4 v2, s[60:61]
	s_mov_b32 m0, s70
	s_add_i32 s71, s53, 0x4000
	global_load_lds_dwordx4 v3, s[60:61]
	v_mov_b32_e32 v2, v128
	v_mov_b32_e32 v3, v130
	s_mov_b32 m0, s71
	s_add_i32 s72, s53, 0x6000
	v_ashrrev_i32_e32 v0, 8, v132
	s_mov_b32 m0, s72
	v_cmp_eq_u32_e32 vcc, 1, v0
	s_and_saveexec_b64 s[66:67], vcc
	s_cbranch_execz .Lh1_137
	s_barrier
.Lh1_137:
	s_or_b64 exec, exec, s[66:67]
	v_mov_b32_e32 v196, v128
	v_mov_b32_e32 v2, v130
	s_waitcnt vmcnt(2)
	s_barrier
	s_add_i32 s66, s53, 0x18000
	v_lshl_add_u64 v[4:5], s[64:65], 0, v[196:197]
	v_mov_b32_e32 v3, v197
	v_lshl_add_u64 v[4:5], v[4:5], 0, s[94:95]
	s_mov_b32 m0, s66
	v_lshl_add_u64 v[2:3], s[64:65], 0, v[2:3]
	s_add_i32 s64, s53, 0x1a000
	global_load_lds_dwordx4 v[4:5], off
	v_lshl_add_u64 v[2:3], v[2:3], 0, s[94:95]
	s_mov_b32 m0, s64
	v_mov_b32_e32 v196, v128
	global_load_lds_dwordx4 v[2:3], off
	v_mov_b32_e32 v2, v130
	s_add_i32 s65, s53, 0x8000
	v_lshl_add_u64 v[4:5], s[62:63], 0, v[196:197]
	v_mov_b32_e32 v3, v197
	v_lshl_add_u64 v[4:5], v[4:5], 0, s[94:95]
	s_mov_b32 m0, s65
	v_lshl_add_u64 v[2:3], s[62:63], 0, v[2:3]
	s_add_i32 s67, s53, 0xa000
	global_load_lds_dwordx4 v[4:5], off
	v_lshl_add_u64 v[2:3], v[2:3], 0, s[94:95]
	s_mov_b32 m0, s67
	v_mov_b32_e32 v196, v128
	global_load_lds_dwordx4 v[2:3], off
	v_mov_b32_e32 v2, v130
	s_add_i32 s33, s53, 0x1c000
	v_lshl_add_u64 v[4:5], s[60:61], 0, v[196:197]
	v_mov_b32_e32 v3, v197
	v_lshl_add_u64 v[4:5], v[4:5], 0, s[94:95]
	s_mov_b32 m0, s33
	v_lshl_add_u64 v[2:3], s[60:61], 0, v[2:3]
	s_add_i32 s73, s53, 0x1e000
	global_load_lds_dwordx4 v[4:5], off
	v_lshl_add_u64 v[2:3], v[2:3], 0, s[94:95]
	s_mov_b32 m0, s73
	v_and_b32_e32 v6, 15, v132
	global_load_lds_dwordx4 v[2:3], off
	v_and_b32_e32 v7, 48, v132
	v_lshlrev_b32_e32 v2, 6, v6
	v_lshlrev_b32_e32 v4, 2, v132
	v_or_b32_e32 v3, v2, v7
	v_and_b32_e32 v4, 32, v4
	s_mov_b32 s36, 0x10000
	v_bitop3_b32 v5, v3, s36, v4 bitop3:0xde
	s_mov_b32 s36, 0x14000
	v_lshlrev_b32_e32 v9, 13, v0
	v_lshlrev_b32_e32 v0, 6, v132
	s_waitcnt vmcnt(6)
	v_lshlrev_b32_e32 v1, 12, v1
	v_bitop3_b32 v6, v3, s36, v4 bitop3:0xde
	s_mov_b32 s36, 0x1c000
	v_and_b32_e32 v0, 0x3c0, v0
	v_readlane_b32 s44, v253, 1
	v_and_b32_e32 v1, 0x3000, v1
	v_bitop3_b32 v2, v2, v4, v7 bitop3:0x36
	v_bitop3_b32 v8, v3, s2, v4 bitop3:0xde
	v_bitop3_b32 v3, v3, s36, v4 bitop3:0xde
	v_bitop3_b32 v4, v0, v4, v7 bitop3:0x36
	v_or_b32_e32 v7, 0x800, v9
	v_or_b32_e32 v10, 0x1000, v9
	v_or_b32_e32 v11, 0x1800, v9
	s_add_u32 s36, s4, s28
	v_mov_b32_e32 v0, 0
	v_readlane_b32 s45, v253, 2
	v_readlane_b32 s46, v253, 3
	v_readlane_b32 s47, v253, 4
	v_readlane_b32 s48, v253, 5
	v_readlane_b32 s49, v253, 6
	v_readlane_b32 s50, v253, 7
	v_readlane_b32 s51, v253, 8
	s_addc_u32 s37, s5, s29
	s_mov_b32 s38, -2
	v_add_u32_e32 v129, v5, v1
	v_add_u32_e32 v136, v2, v9
	v_add_u32_e32 v135, v4, v7
	v_add_u32_e32 v134, v4, v10
	v_add_u32_e32 v133, v4, v11
	v_add_u32_e32 v139, v6, v1
	v_add_u32_e32 v138, v8, v1
	v_add_u32_e32 v137, v3, v1
	s_mov_b64 s[60:61], s[50:51]
	v_mov_b32_e32 v1, v0
	v_mov_b32_e32 v2, v0
	v_mov_b32_e32 v3, v0
	v_mov_b32_e32 v4, v0
	v_mov_b32_e32 v5, v0
	v_mov_b32_e32 v6, v0
	v_mov_b32_e32 v7, v0
	v_mov_b32_e32 v8, v0
	v_mov_b32_e32 v9, v0
	v_mov_b32_e32 v10, v0
	v_mov_b32_e32 v11, v0
	v_mov_b32_e32 v12, v0
	v_mov_b32_e32 v13, v0
	v_mov_b32_e32 v14, v0
	v_mov_b32_e32 v15, v0
	v_mov_b32_e32 v16, v0
	v_mov_b32_e32 v17, v0
	v_mov_b32_e32 v18, v0
	v_mov_b32_e32 v19, v0
	v_mov_b32_e32 v20, v0
	v_mov_b32_e32 v21, v0
	v_mov_b32_e32 v22, v0
	v_mov_b32_e32 v23, v0
	v_mov_b32_e32 v24, v0
	v_mov_b32_e32 v25, v0
	v_mov_b32_e32 v26, v0
	v_mov_b32_e32 v27, v0
	v_mov_b32_e32 v28, v0
	v_mov_b32_e32 v29, v0
	v_mov_b32_e32 v30, v0
	v_mov_b32_e32 v31, v0
	v_mov_b32_e32 v32, v0
	v_mov_b32_e32 v33, v0
	v_mov_b32_e32 v34, v0
	v_mov_b32_e32 v35, v0
	v_mov_b32_e32 v36, v0
	v_mov_b32_e32 v37, v0
	v_mov_b32_e32 v38, v0
	v_mov_b32_e32 v39, v0
	v_mov_b32_e32 v40, v0
	v_mov_b32_e32 v41, v0
	v_mov_b32_e32 v42, v0
	v_mov_b32_e32 v43, v0
	v_mov_b32_e32 v44, v0
	v_mov_b32_e32 v45, v0
	v_mov_b32_e32 v46, v0
	v_mov_b32_e32 v47, v0
	v_mov_b32_e32 v48, v0
	v_mov_b32_e32 v49, v0
	v_mov_b32_e32 v50, v0
	v_mov_b32_e32 v51, v0
	v_mov_b32_e32 v52, v0
	v_mov_b32_e32 v53, v0
	v_mov_b32_e32 v54, v0
	v_mov_b32_e32 v55, v0
	v_mov_b32_e32 v56, v0
	v_mov_b32_e32 v57, v0
	v_mov_b32_e32 v58, v0
	v_mov_b32_e32 v59, v0
	v_mov_b32_e32 v60, v0
	v_mov_b32_e32 v61, v0
	v_mov_b32_e32 v62, v0
	v_mov_b32_e32 v63, v0
	v_mov_b32_e32 v64, v0
	v_mov_b32_e32 v65, v0
	v_mov_b32_e32 v66, v0
	v_mov_b32_e32 v67, v0
	v_mov_b32_e32 v68, v0
	v_mov_b32_e32 v69, v0
	v_mov_b32_e32 v70, v0
	v_mov_b32_e32 v71, v0
	v_mov_b32_e32 v72, v0
	v_mov_b32_e32 v73, v0
	v_mov_b32_e32 v74, v0
	v_mov_b32_e32 v75, v0
	v_mov_b32_e32 v76, v0
	v_mov_b32_e32 v77, v0
	v_mov_b32_e32 v78, v0
	v_mov_b32_e32 v79, v0
	v_mov_b32_e32 v80, v0
	v_mov_b32_e32 v81, v0
	v_mov_b32_e32 v82, v0
	v_mov_b32_e32 v83, v0
	v_mov_b32_e32 v84, v0
	v_mov_b32_e32 v85, v0
	v_mov_b32_e32 v86, v0
	v_mov_b32_e32 v87, v0
	v_mov_b32_e32 v88, v0
	v_mov_b32_e32 v89, v0
	v_mov_b32_e32 v90, v0
	v_mov_b32_e32 v91, v0
	v_mov_b32_e32 v92, v0
	v_mov_b32_e32 v93, v0
	v_mov_b32_e32 v94, v0
	v_mov_b32_e32 v95, v0
	v_mov_b32_e32 v96, v0
	v_mov_b32_e32 v97, v0
	v_mov_b32_e32 v98, v0
	v_mov_b32_e32 v99, v0
	v_mov_b32_e32 v100, v0
	v_mov_b32_e32 v101, v0
	v_mov_b32_e32 v102, v0
	v_mov_b32_e32 v103, v0
	v_mov_b32_e32 v104, v0
	v_mov_b32_e32 v105, v0
	v_mov_b32_e32 v106, v0
	v_mov_b32_e32 v107, v0
	v_mov_b32_e32 v108, v0
	v_mov_b32_e32 v109, v0
	v_mov_b32_e32 v110, v0
	v_mov_b32_e32 v111, v0
	v_mov_b32_e32 v112, v0
	v_mov_b32_e32 v113, v0
	v_mov_b32_e32 v114, v0
	v_mov_b32_e32 v115, v0
	v_mov_b32_e32 v116, v0
	v_mov_b32_e32 v117, v0
	v_mov_b32_e32 v118, v0
	v_mov_b32_e32 v119, v0
	v_mov_b32_e32 v120, v0
	v_mov_b32_e32 v121, v0
	v_mov_b32_e32 v122, v0
	v_mov_b32_e32 v123, v0
	v_mov_b32_e32 v124, v0
	v_mov_b32_e32 v125, v0
	v_mov_b32_e32 v126, v0
	v_mov_b32_e32 v127, v0
	s_mov_b64 s[44:45], 0x2c480080
	s_mov_b64 s[46:47], 0x6c00100
	s_mov_b64 s[48:49], 0x2c400100
	s_mov_b64 s[50:51], 0x6c80100
	s_mov_b64 s[74:75], 0x2c480100
	s_mov_b64 s[90:91], 0x6c00180
	s_mov_b64 s[92:93], 0x2c400180
	s_mov_b64 s[96:97], 0x6c80180
	s_barrier
.Lh1_loop:
	ds_read_b128 v[140:143], v129
	ds_read_b128 v[144:147], v129 offset:1024
	ds_read_b128 v[148:151], v129 offset:2048
	ds_read_b128 v[152:155], v129 offset:3072
	s_add_u32 s28, s60, s56
	v_mov_b32_e32 v196, v128
	v_mov_b32_e32 v188, v130
	s_addc_u32 s29, s61, s57
	ds_read_b128 v[156:159], v136
	ds_read_b128 v[160:163], v136 offset:1024
	ds_read_b128 v[164:167], v135
	ds_read_b128 v[168:171], v135 offset:1024
	ds_read_b128 v[172:175], v134
	ds_read_b128 v[176:179], v134 offset:1024
	ds_read_b128 v[180:183], v133
	ds_read_b128 v[184:187], v133 offset:1024
	s_add_i32 s40, s53, 0xc000
	v_lshl_add_u64 v[190:191], s[28:29], 0, v[196:197]
	v_mov_b32_e32 v189, v197
	v_lshl_add_u64 v[190:191], v[190:191], 0, s[44:45]
	s_mov_b32 m0, s40
	v_lshl_add_u64 v[188:189], s[28:29], 0, v[188:189]
	s_add_i32 s39, s53, 0xe000
	v_lshl_add_u64 v[188:189], v[188:189], 0, s[44:45]
	s_mov_b32 m0, s39
	s_nop 0
	s_waitcnt lgkmcnt(8)
	s_barrier
	s_waitcnt lgkmcnt(0)
	s_setprio 1
	s_waitcnt lgkmcnt(0)
	v_mfma_f32_16x16x32_bf16 v[124:127], v[140:143], v[156:159], v[124:127]
	v_mfma_f32_16x16x32_bf16 v[120:123], v[148:151], v[156:159], v[120:123]
	v_mfma_f32_16x16x32_bf16 v[116:119], v[140:143], v[164:167], v[116:119]
	v_mfma_f32_16x16x32_bf16 v[112:115], v[148:151], v[164:167], v[112:115]
	v_mfma_f32_16x16x32_bf16 v[108:111], v[140:143], v[172:175], v[108:111]
	v_mfma_f32_16x16x32_bf16 v[104:107], v[148:151], v[172:175], v[104:107]
	v_mfma_f32_16x16x32_bf16 v[100:103], v[140:143], v[180:183], v[100:103]
	v_mfma_f32_16x16x32_bf16 v[96:99], v[148:151], v[180:183], v[96:99]
	v_mfma_f32_16x16x32_bf16 v[124:127], v[144:147], v[160:163], v[124:127]
	v_mfma_f32_16x16x32_bf16 v[120:123], v[152:155], v[160:163], v[120:123]
	v_mfma_f32_16x16x32_bf16 v[116:119], v[144:147], v[168:171], v[116:119]
	v_mfma_f32_16x16x32_bf16 v[112:115], v[152:155], v[168:171], v[112:115]
	v_mfma_f32_16x16x32_bf16 v[108:111], v[144:147], v[176:179], v[108:111]
	v_mfma_f32_16x16x32_bf16 v[104:107], v[152:155], v[176:179], v[104:107]
	v_mfma_f32_16x16x32_bf16 v[100:103], v[144:147], v[184:187], v[100:103]
	v_mfma_f32_16x16x32_bf16 v[96:99], v[152:155], v[184:187], v[96:99]
	s_setprio 0
	s_barrier
	s_add_u32 s62, s60, s36
	v_mov_b32_e32 v196, v128
	v_mov_b32_e32 v210, v130
	s_addc_u32 s63, s61, s37
	ds_read_b128 v[188:191], v139
	ds_read_b128 v[192:195], v139 offset:1024
	ds_read_b128 v[202:205], v139 offset:2048
	ds_read_b128 v[206:209], v139 offset:3072
	v_mov_b32_e32 v211, v197
	v_lshl_add_u64 v[212:213], s[62:63], 0, v[196:197]
	s_mov_b32 m0, s68
	v_lshl_add_u64 v[212:213], v[212:213], 0, s[46:47]
	v_lshl_add_u64 v[210:211], s[62:63], 0, v[210:211]
	global_load_lds_dwordx4 v[212:213], off
	v_lshl_add_u64 v[210:211], v[210:211], 0, s[46:47]
	s_mov_b32 m0, s69
	s_nop 0
	global_load_lds_dwordx4 v[210:211], off
	s_barrier
	s_waitcnt lgkmcnt(0)
	s_setprio 1
	s_waitcnt lgkmcnt(0)
	v_mfma_f32_16x16x32_bf16 v[92:95], v[188:191], v[156:159], v[92:95]
	v_mfma_f32_16x16x32_bf16 v[88:91], v[202:205], v[156:159], v[88:91]
	v_mfma_f32_16x16x32_bf16 v[84:87], v[188:191], v[164:167], v[84:87]
	v_mfma_f32_16x16x32_bf16 v[80:83], v[202:205], v[164:167], v[80:83]
	v_mfma_f32_16x16x32_bf16 v[76:79], v[188:191], v[172:175], v[76:79]
	v_mfma_f32_16x16x32_bf16 v[72:75], v[202:205], v[172:175], v[72:75]
	v_mfma_f32_16x16x32_bf16 v[68:71], v[188:191], v[180:183], v[68:71]
	v_mfma_f32_16x16x32_bf16 v[64:67], v[202:205], v[180:183], v[64:67]
	v_mfma_f32_16x16x32_bf16 v[92:95], v[192:195], v[160:163], v[92:95]
	v_mfma_f32_16x16x32_bf16 v[88:91], v[206:209], v[160:163], v[88:91]
	v_mfma_f32_16x16x32_bf16 v[84:87], v[192:195], v[168:171], v[84:87]
	v_mfma_f32_16x16x32_bf16 v[80:83], v[206:209], v[168:171], v[80:83]
	v_mfma_f32_16x16x32_bf16 v[76:79], v[192:195], v[176:179], v[76:79]
	v_mfma_f32_16x16x32_bf16 v[72:75], v[206:209], v[176:179], v[72:75]
	v_mfma_f32_16x16x32_bf16 v[68:71], v[192:195], v[184:187], v[68:71]
	v_mfma_f32_16x16x32_bf16 v[64:67], v[206:209], v[184:187], v[64:67]
	s_setprio 0
	v_mov_b32_e32 v196, v128
	v_mov_b32_e32 v210, v130
	s_barrier
	v_mov_b32_e32 v211, v197
	v_lshl_add_u64 v[212:213], s[28:29], 0, v[196:197]
	s_mov_b32 m0, s53
	v_lshl_add_u64 v[212:213], v[212:213], 0, s[48:49]
	v_lshl_add_u64 v[210:211], s[28:29], 0, v[210:211]
	global_load_lds_dwordx4 v[212:213], off
	v_lshl_add_u64 v[210:211], v[210:211], 0, s[48:49]
	s_mov_b32 m0, s11
	s_nop 0
	global_load_lds_dwordx4 v[210:211], off
	s_barrier
	s_waitcnt lgkmcnt(0)
	s_setprio 1
	s_waitcnt lgkmcnt(0)
	s_setprio 0
	s_barrier
	v_mov_b32_e32 v196, v128
	v_mov_b32_e32 v140, v130
	v_mov_b32_e32 v141, v197
	v_lshl_add_u64 v[142:143], s[62:63], 0, v[196:197]
	s_mov_b32 m0, s9
	v_lshl_add_u64 v[142:143], v[142:143], 0, s[50:51]
	v_lshl_add_u64 v[140:141], s[62:63], 0, v[140:141]
	global_load_lds_dwordx4 v[142:143], off
	v_lshl_add_u64 v[140:141], v[140:141], 0, s[50:51]
	s_mov_b32 m0, s70
	s_nop 0
	global_load_lds_dwordx4 v[140:141], off
	s_waitcnt vmcnt(6)
	s_barrier
	s_setprio 1
	s_setprio 0
	s_barrier
	ds_read_b128 v[140:143], v138
	ds_read_b128 v[144:147], v138 offset:1024
	ds_read_b128 v[148:151], v138 offset:2048
	ds_read_b128 v[152:155], v138 offset:3072
	v_mov_b32_e32 v196, v128
	v_mov_b32_e32 v188, v130
	ds_read_b128 v[156:159], v136 offset:32768
	ds_read_b128 v[160:163], v136 offset:33792
	ds_read_b128 v[164:167], v135 offset:32768
	ds_read_b128 v[168:171], v135 offset:33792
	ds_read_b128 v[172:175], v134 offset:32768
	ds_read_b128 v[176:179], v134 offset:33792
	ds_read_b128 v[180:183], v133 offset:32768
	ds_read_b128 v[184:187], v133 offset:33792
	v_mov_b32_e32 v189, v197
	v_lshl_add_u64 v[190:191], s[28:29], 0, v[196:197]
	s_mov_b32 m0, s71
	v_lshl_add_u64 v[190:191], v[190:191], 0, s[74:75]
	v_lshl_add_u64 v[188:189], s[28:29], 0, v[188:189]
	v_lshl_add_u64 v[188:189], v[188:189], 0, s[74:75]
	s_mov_b32 m0, s72
	s_nop 0
	s_waitcnt lgkmcnt(8)
	s_barrier
	s_waitcnt lgkmcnt(0)
	s_setprio 1
	s_waitcnt lgkmcnt(0)
	v_mfma_f32_16x16x32_bf16 v[124:127], v[140:143], v[156:159], v[124:127]
	v_mfma_f32_16x16x32_bf16 v[120:123], v[148:151], v[156:159], v[120:123]
	v_mfma_f32_16x16x32_bf16 v[116:119], v[140:143], v[164:167], v[116:119]
	v_mfma_f32_16x16x32_bf16 v[112:115], v[148:151], v[164:167], v[112:115]
	v_mfma_f32_16x16x32_bf16 v[108:111], v[140:143], v[172:175], v[108:111]
	v_mfma_f32_16x16x32_bf16 v[104:107], v[148:151], v[172:175], v[104:107]
	v_mfma_f32_16x16x32_bf16 v[100:103], v[140:143], v[180:183], v[100:103]
	v_mfma_f32_16x16x32_bf16 v[96:99], v[148:151], v[180:183], v[96:99]
	v_mfma_f32_16x16x32_bf16 v[124:127], v[144:147], v[160:163], v[124:127]
	v_mfma_f32_16x16x32_bf16 v[120:123], v[152:155], v[160:163], v[120:123]
	v_mfma_f32_16x16x32_bf16 v[116:119], v[144:147], v[168:171], v[116:119]
	v_mfma_f32_16x16x32_bf16 v[112:115], v[152:155], v[168:171], v[112:115]
	v_mfma_f32_16x16x32_bf16 v[108:111], v[144:147], v[176:179], v[108:111]
	v_mfma_f32_16x16x32_bf16 v[104:107], v[152:155], v[176:179], v[104:107]
	v_mfma_f32_16x16x32_bf16 v[100:103], v[144:147], v[184:187], v[100:103]
	v_mfma_f32_16x16x32_bf16 v[96:99], v[152:155], v[184:187], v[96:99]
	s_setprio 0
	s_barrier
	v_mov_b32_e32 v196, v128
	v_mov_b32_e32 v210, v130
	ds_read_b128 v[188:191], v137
	ds_read_b128 v[192:195], v137 offset:1024
	ds_read_b128 v[202:205], v137 offset:2048
	ds_read_b128 v[206:209], v137 offset:3072
	v_mov_b32_e32 v211, v197
	v_lshl_add_u64 v[212:213], s[62:63], 0, v[196:197]
	s_mov_b32 m0, s66
	v_lshl_add_u64 v[212:213], v[212:213], 0, s[90:91]
	v_lshl_add_u64 v[210:211], s[62:63], 0, v[210:211]
	global_load_lds_dwordx4 v[212:213], off
	v_lshl_add_u64 v[210:211], v[210:211], 0, s[90:91]
	s_mov_b32 m0, s64
	s_nop 0
	global_load_lds_dwordx4 v[210:211], off
	s_barrier
	s_waitcnt lgkmcnt(0)
	s_setprio 1
	s_waitcnt lgkmcnt(0)
	v_mfma_f32_16x16x32_bf16 v[92:95], v[188:191], v[156:159], v[92:95]
	v_mfma_f32_16x16x32_bf16 v[88:91], v[202:205], v[156:159], v[88:91]
	v_mfma_f32_16x16x32_bf16 v[84:87], v[188:191], v[164:167], v[84:87]
	v_mfma_f32_16x16x32_bf16 v[80:83], v[202:205], v[164:167], v[80:83]
	v_mfma_f32_16x16x32_bf16 v[76:79], v[188:191], v[172:175], v[76:79]
	v_mfma_f32_16x16x32_bf16 v[72:75], v[202:205], v[172:175], v[72:75]
	v_mfma_f32_16x16x32_bf16 v[68:71], v[188:191], v[180:183], v[68:71]
	v_mfma_f32_16x16x32_bf16 v[64:67], v[202:205], v[180:183], v[64:67]
	v_mfma_f32_16x16x32_bf16 v[92:95], v[192:195], v[160:163], v[92:95]
	v_mfma_f32_16x16x32_bf16 v[88:91], v[206:209], v[160:163], v[88:91]
	v_mfma_f32_16x16x32_bf16 v[84:87], v[192:195], v[168:171], v[84:87]
	v_mfma_f32_16x16x32_bf16 v[80:83], v[206:209], v[168:171], v[80:83]
	v_mfma_f32_16x16x32_bf16 v[76:79], v[192:195], v[176:179], v[76:79]
	v_mfma_f32_16x16x32_bf16 v[72:75], v[206:209], v[176:179], v[72:75]
	v_mfma_f32_16x16x32_bf16 v[68:71], v[192:195], v[184:187], v[68:71]
	v_mfma_f32_16x16x32_bf16 v[64:67], v[206:209], v[184:187], v[64:67]
	s_setprio 0
	v_mov_b32_e32 v196, v128
	v_mov_b32_e32 v210, v130
	s_barrier
	v_mov_b32_e32 v211, v197
	v_lshl_add_u64 v[212:213], s[28:29], 0, v[196:197]
	s_mov_b32 m0, s65
	v_lshl_add_u64 v[212:213], v[212:213], 0, s[92:93]
	v_lshl_add_u64 v[210:211], s[28:29], 0, v[210:211]
	global_load_lds_dwordx4 v[212:213], off
	v_lshl_add_u64 v[210:211], v[210:211], 0, s[92:93]
	s_mov_b32 m0, s67
	s_nop 0
	global_load_lds_dwordx4 v[210:211], off
	s_barrier
	s_waitcnt lgkmcnt(0)
	s_setprio 1
	s_waitcnt lgkmcnt(0)
	s_setprio 0
	s_barrier
	v_mov_b32_e32 v196, v128
	v_mov_b32_e32 v140, v130
	v_mov_b32_e32 v141, v197
	v_lshl_add_u64 v[142:143], s[62:63], 0, v[196:197]
	s_mov_b32 m0, s33
	v_lshl_add_u64 v[142:143], v[142:143], 0, s[96:97]
	v_lshl_add_u64 v[140:141], s[62:63], 0, v[140:141]
	global_load_lds_dwordx4 v[142:143], off
	v_lshl_add_u64 v[140:141], v[140:141], 0, s[96:97]
	s_mov_b32 m0, s73
	s_nop 0
	global_load_lds_dwordx4 v[140:141], off
	s_waitcnt vmcnt(6)
	s_barrier
	s_setprio 1
	s_setprio 0
	s_add_i32 s38, s38, 2
	s_add_u32 s60, s60, 0x100
	s_addc_u32 s61, s61, 0
	s_cmp_lt_u32 s38, 28
	s_barrier
	s_cbranch_scc1 .Lh1_loop
	ds_read_b128 v[140:143], v129
	ds_read_b128 v[144:147], v129 offset:1024
	ds_read_b128 v[148:151], v129 offset:2048
	ds_read_b128 v[152:155], v129 offset:3072
	ds_read_b128 v[156:159], v136
	ds_read_b128 v[160:163], v136 offset:1024
	ds_read_b128 v[164:167], v135
	ds_read_b128 v[168:171], v135 offset:1024
	ds_read_b128 v[172:175], v134
	ds_read_b128 v[176:179], v134 offset:1024
	ds_read_b128 v[180:183], v133
	ds_read_b128 v[184:187], v133 offset:1024
	v_mov_b32_e32 v129, v197
	v_lshl_add_u64 v[128:129], s[58:59], 0, v[128:129]
	s_mov_b64 s[28:29], 0xf80
	s_mov_b32 m0, s40
	v_lshl_add_u64 v[128:129], v[128:129], 0, s[28:29]
	v_mov_b32_e32 v131, v197
	v_lshl_add_u64 v[128:129], s[58:59], 0, v[130:131]
	v_lshl_add_u64 v[128:129], v[128:129], 0, s[28:29]
	s_mov_b32 m0, s39
	s_nop 0
	s_barrier
	s_waitcnt lgkmcnt(0)
	s_setprio 1
	s_waitcnt lgkmcnt(0)
	v_mfma_f32_16x16x32_bf16 v[124:127], v[140:143], v[156:159], v[124:127]
	v_mfma_f32_16x16x32_bf16 v[120:123], v[148:151], v[156:159], v[120:123]
	v_mfma_f32_16x16x32_bf16 v[116:119], v[140:143], v[164:167], v[116:119]
	v_mfma_f32_16x16x32_bf16 v[112:115], v[148:151], v[164:167], v[112:115]
	v_mfma_f32_16x16x32_bf16 v[108:111], v[140:143], v[172:175], v[108:111]
	v_mfma_f32_16x16x32_bf16 v[100:103], v[140:143], v[180:183], v[100:103]
	v_mfma_f32_16x16x32_bf16 v[96:99], v[148:151], v[180:183], v[96:99]
	v_mfma_f32_16x16x32_bf16 v[124:127], v[144:147], v[160:163], v[124:127]
	v_mfma_f32_16x16x32_bf16 v[120:123], v[152:155], v[160:163], v[120:123]
	v_mfma_f32_16x16x32_bf16 v[116:119], v[144:147], v[168:171], v[116:119]
	v_mfma_f32_16x16x32_bf16 v[112:115], v[152:155], v[168:171], v[112:115]
	v_mfma_f32_16x16x32_bf16 v[108:111], v[144:147], v[176:179], v[108:111]
	v_mfma_f32_16x16x32_bf16 v[104:107], v[148:151], v[172:175], v[104:107]
	v_mfma_f32_16x16x32_bf16 v[100:103], v[144:147], v[184:187], v[100:103]
	v_mfma_f32_16x16x32_bf16 v[96:99], v[152:155], v[184:187], v[96:99]
	v_mfma_f32_16x16x32_bf16 v[128:131], v[152:155], v[176:179], v[104:107]
	s_setprio 0
	s_barrier
	s_nop 2
	ds_read_b128 v[104:107], v139
	ds_read_b128 v[188:191], v139 offset:1024
	ds_read_b128 v[192:195], v139 offset:2048
	ds_read_b128 v[202:205], v139 offset:3072
	s_barrier
	s_waitcnt lgkmcnt(0)
	s_setprio 1
	s_waitcnt lgkmcnt(0)
	v_mfma_f32_16x16x32_bf16 v[92:95], v[104:107], v[156:159], v[92:95]
	v_mfma_f32_16x16x32_bf16 v[84:87], v[104:107], v[164:167], v[84:87]
	v_mfma_f32_16x16x32_bf16 v[76:79], v[104:107], v[172:175], v[76:79]
	v_mfma_f32_16x16x32_bf16 v[68:71], v[104:107], v[180:183], v[68:71]
	v_mfma_f32_16x16x32_bf16 v[64:67], v[192:195], v[180:183], v[64:67]
	v_mfma_f32_16x16x32_bf16 v[92:95], v[188:191], v[160:163], v[92:95]
	v_mfma_f32_16x16x32_bf16 v[88:91], v[192:195], v[156:159], v[88:91]
	v_mfma_f32_16x16x32_bf16 v[84:87], v[188:191], v[168:171], v[84:87]
	v_mfma_f32_16x16x32_bf16 v[80:83], v[192:195], v[164:167], v[80:83]
	v_mfma_f32_16x16x32_bf16 v[76:79], v[188:191], v[176:179], v[76:79]
	v_mfma_f32_16x16x32_bf16 v[72:75], v[192:195], v[172:175], v[72:75]
	v_mfma_f32_16x16x32_bf16 v[68:71], v[188:191], v[184:187], v[68:71]
	v_mfma_f32_16x16x32_bf16 v[64:67], v[202:205], v[184:187], v[64:67]
	v_mfma_f32_16x16x32_bf16 v[156:159], v[202:205], v[160:163], v[88:91]
	v_mfma_f32_16x16x32_bf16 v[160:163], v[202:205], v[168:171], v[80:83]
	v_mfma_f32_16x16x32_bf16 v[164:167], v[202:205], v[176:179], v[72:75]
	s_setprio 0
	s_barrier
	s_nop 0
	s_waitcnt vmcnt(2)
	s_barrier
	s_waitcnt lgkmcnt(0)
	s_setprio 1
	s_waitcnt lgkmcnt(0)
	s_setprio 0
	s_setprio 1
	s_setprio 0
	s_barrier
	ds_read_b128 v[16:19], v138
	ds_read_b128 v[180:183], v138 offset:1024
	ds_read_b128 v[184:187], v138 offset:2048
	ds_read_b128 v[188:191], v138 offset:3072
	ds_read_b128 v[0:3], v136 offset:32768
	ds_read_b128 v[4:7], v136 offset:33792
	ds_read_b128 v[8:11], v135 offset:32768
	ds_read_b128 v[12:15], v135 offset:33792
	ds_read_b128 v[44:47], v134 offset:32768
	ds_read_b128 v[192:195], v134 offset:33792
	ds_read_b128 v[202:205], v133 offset:32768
	ds_read_b128 v[218:221], v133 offset:33792
	s_waitcnt vmcnt(0)
	s_barrier
	s_waitcnt lgkmcnt(0)
	s_setprio 1
	s_waitcnt lgkmcnt(0)
	v_mfma_f32_16x16x32_bf16 v[28:31], v[16:19], v[0:3], v[124:127]
	v_mfma_f32_16x16x32_bf16 v[52:55], v[180:183], v[4:7], v[28:31]
	v_mfma_f32_16x16x32_bf16 v[28:31], v[184:187], v[0:3], v[120:123]
	v_mfma_f32_16x16x32_bf16 v[104:107], v[188:191], v[4:7], v[28:31]
	v_mfma_f32_16x16x32_bf16 v[28:31], v[16:19], v[8:11], v[116:119]
	v_mfma_f32_16x16x32_bf16 v[72:75], v[180:183], v[12:15], v[28:31]
	v_mfma_f32_16x16x32_bf16 v[28:31], v[184:187], v[8:11], v[112:115]
	v_mfma_f32_16x16x32_bf16 v[116:119], v[188:191], v[12:15], v[28:31]
	v_mfma_f32_16x16x32_bf16 v[28:31], v[16:19], v[44:47], v[108:111]
	v_mfma_f32_16x16x32_bf16 v[80:83], v[180:183], v[192:195], v[28:31]
	v_mfma_f32_16x16x32_bf16 v[28:31], v[184:187], v[44:47], v[128:131]
	v_mfma_f32_16x16x32_bf16 v[108:111], v[188:191], v[192:195], v[28:31]
	v_mfma_f32_16x16x32_bf16 v[28:31], v[16:19], v[202:205], v[100:103]
	v_mfma_f32_16x16x32_bf16 v[88:91], v[180:183], v[218:221], v[28:31]
	v_mfma_f32_16x16x32_bf16 v[28:31], v[184:187], v[202:205], v[96:99]
	v_mfma_f32_16x16x32_bf16 v[96:99], v[188:191], v[218:221], v[28:31]
	s_setprio 0
	s_barrier
	ds_read_b128 v[128:131], v137
	ds_read_b128 v[222:225], v137 offset:1024
	ds_read_b128 v[228:231], v137 offset:2048
	ds_read_b128 v[232:235], v137 offset:3072
	s_waitcnt vmcnt(0)
	s_barrier
	s_waitcnt lgkmcnt(0)
	s_setprio 1
	s_waitcnt lgkmcnt(0)
	v_mfma_f32_16x16x32_bf16 v[28:31], v[128:131], v[0:3], v[92:95]
	v_mfma_f32_16x16x32_bf16 v[0:3], v[228:231], v[0:3], v[156:159]
	v_mfma_f32_16x16x32_bf16 v[28:31], v[222:225], v[4:7], v[28:31]
	v_mfma_f32_16x16x32_bf16 v[0:3], v[232:235], v[4:7], v[0:3]
	v_mfma_f32_16x16x32_bf16 v[4:7], v[128:131], v[8:11], v[84:87]
	v_mfma_f32_16x16x32_bf16 v[36:39], v[222:225], v[12:15], v[4:7]
	v_mfma_f32_16x16x32_bf16 v[4:7], v[228:231], v[8:11], v[160:163]
	v_mfma_f32_16x16x32_bf16 v[4:7], v[232:235], v[12:15], v[4:7]
	v_mfma_f32_16x16x32_bf16 v[8:11], v[128:131], v[44:47], v[76:79]
	v_mfma_f32_16x16x32_bf16 v[12:15], v[128:131], v[202:205], v[68:71]
	v_mfma_f32_16x16x32_bf16 v[40:43], v[222:225], v[192:195], v[8:11]
	v_mfma_f32_16x16x32_bf16 v[8:11], v[228:231], v[44:47], v[164:167]
	v_mfma_f32_16x16x32_bf16 v[44:47], v[222:225], v[218:221], v[12:15]
	v_mfma_f32_16x16x32_bf16 v[12:15], v[228:231], v[202:205], v[64:67]
	v_mfma_f32_16x16x32_bf16 v[8:11], v[232:235], v[192:195], v[8:11]
	v_mfma_f32_16x16x32_bf16 v[12:15], v[232:235], v[218:221], v[12:15]
	s_setprio 0
	s_barrier
	s_barrier
	s_waitcnt lgkmcnt(0)
	s_setprio 1
	s_waitcnt lgkmcnt(0)
	s_setprio 0
	s_setprio 1
	s_setprio 0
	s_movk_i32 s9, 0x100
	v_cmp_gt_u32_e32 vcc, s9, v132
	s_barrier
	s_and_saveexec_b64 s[28:29], vcc
	s_cbranch_execz .Lh1_epi
	s_barrier
.Lh1_epi:
	s_or_b64 exec, exec, s[28:29]
	s_cmp_lt_i32 s52, 16
	s_cselect_b64 s[36:37], -1, 0
	s_add_i32 s9, s10, 0xfffff000
	s_ashr_i32 s9, s9, 10
	s_and_b64 s[28:29], s[36:37], exec
	s_mov_b32 s28, -1
	s_cselect_b32 s9, 8, s9
	v_mbcnt_lo_u32_b32 v128, s28, 0
	v_mbcnt_hi_u32_b32 v128, s28, v128
	v_add_u32_e32 v134, s43, v128
	v_readlane_b32 s11, v255, 8
	v_lshrrev_b32_e32 v128, 1, v134
	v_and_b32_e32 v128, 0x60, v128
	v_lshrrev_b32_e32 v129, 2, v134
	v_and_or_b32 v196, v129, 12, v128
	v_or_b32_e32 v130, s6, v196
	v_ashrrev_i32_e32 v131, 31, v130
	v_lshlrev_b64 v[132:133], 2, v[130:131]
	v_ashrrev_i32_e32 v131, 2, v134
	v_and_b32_e32 v131, 0xffffffc0, v131
	v_and_or_b32 v134, v134, 15, s10
	v_add_u32_e32 v134, v134, v131
	v_or_b32_e32 v138, 16, v134
	v_ashrrev_i32_e32 v139, 31, v138
	s_add_i32 s9, s9, s11
	v_readlane_b32 s44, v253, 1
	v_lshlrev_b64 v[168:169], 13, v[138:139]
	v_or_b32_e32 v138, 32, v134
	s_mul_hi_i32 s11, s9, 0xc000
	s_mul_i32 s9, s9, 0xc000
	v_readlane_b32 s50, v253, 7
	v_ashrrev_i32_e32 v139, 31, v138
	v_readlane_b32 s51, v253, 8
	s_add_u32 s9, s50, s9
	v_lshlrev_b64 v[170:171], 13, v[138:139]
	v_or_b32_e32 v138, 48, v134
	s_addc_u32 s11, s51, s11
	v_ashrrev_i32_e32 v139, 31, v138
	s_add_u32 s28, s9, 0x2f764000
	v_lshlrev_b64 v[172:173], 13, v[138:139]
	v_add_u32_e32 v138, 0x80, v134
	s_addc_u32 s29, s11, 0
	v_ashrrev_i32_e32 v139, 31, v138
	s_and_b64 s[36:37], s[36:37], exec
	v_lshlrev_b64 v[174:175], 13, v[138:139]
	v_add_u32_e32 v138, 0x90, v134
	v_readlane_b32 s36, v255, 4
	v_ashrrev_i32_e32 v135, 31, v134
	v_ashrrev_i32_e32 v139, 31, v138
	v_readlane_b32 s9, v254, 16
	v_readlane_b32 s11, v254, 17
	v_readlane_b32 s37, v255, 5
	v_lshlrev_b64 v[164:165], 13, v[134:135]
	v_lshlrev_b64 v[176:177], 13, v[138:139]
	v_add_u32_e32 v138, 0xa0, v134
	v_add_u32_e32 v134, 0xb0, v134
	s_cselect_b32 s9, s12, s9
	s_cselect_b32 s11, s13, s11
	s_and_b64 s[36:37], s[36:37], exec
	v_ashrrev_i32_e32 v135, 31, v134
	v_readlane_b32 s36, v253, 54
	v_lshlrev_b64 v[182:183], 13, v[134:135]
	v_or_b32_e32 v134, 16, v130
	v_readlane_b32 s37, v253, 55
	v_ashrrev_i32_e32 v135, 31, v134
	v_lshl_add_u64 v[184:185], v[134:135], 2, s[28:29]
	v_lshl_add_u64 v[134:135], s[36:37], 0, v[164:165]
	v_lshl_add_u64 v[146:147], v[134:135], 0, v[132:133]
	v_lshl_add_u64 v[134:135], s[36:37], 0, v[168:169]
	v_lshl_add_u64 v[144:145], v[134:135], 0, v[132:133]
	v_lshl_add_u64 v[134:135], s[36:37], 0, v[170:171]
	v_lshl_add_u64 v[142:143], v[134:135], 0, v[132:133]
	v_lshl_add_u64 v[134:135], s[36:37], 0, v[172:173]
	s_cselect_b32 s57, s11, s37
	s_cselect_b32 s56, s9, s36
	v_ashrrev_i32_e32 v139, 31, v138
	v_lshl_add_u64 v[140:141], v[134:135], 0, v[132:133]
	v_lshl_add_u64 v[134:135], s[36:37], 0, v[174:175]
	v_lshl_add_u64 v[136:137], s[56:57], 0, v[132:133]
	v_lshlrev_b64 v[178:179], 13, v[138:139]
	v_lshl_add_u64 v[138:139], v[134:135], 0, v[132:133]
	v_lshl_add_u64 v[134:135], s[36:37], 0, v[176:177]
	v_lshl_add_u64 v[148:149], v[136:137], 0, v[164:165]
	v_lshl_add_u64 v[150:151], v[136:137], 0, v[168:169]
	v_lshl_add_u64 v[152:153], v[136:137], 0, v[170:171]
	v_lshl_add_u64 v[154:155], v[136:137], 0, v[172:173]
	v_lshl_add_u64 v[156:157], v[136:137], 0, v[174:175]
	v_lshl_add_u64 v[158:159], v[136:137], 0, v[176:177]
	v_lshl_add_u64 v[160:161], v[136:137], 0, v[178:179]
	v_lshl_add_u64 v[162:163], v[136:137], 0, v[182:183]
	v_lshl_add_u64 v[136:137], v[134:135], 0, v[132:133]
	v_lshl_add_u64 v[134:135], s[36:37], 0, v[178:179]
	v_lshl_add_u64 v[166:167], s[36:37], 0, v[182:183]
	v_lshl_add_u64 v[128:129], s[28:29], 0, v[132:133]
	v_lshl_add_u64 v[134:135], v[134:135], 0, v[132:133]
	v_lshl_add_u64 v[132:133], v[166:167], 0, v[132:133]
	v_or_b32_e32 v166, s8, v196
	v_ashrrev_i32_e32 v167, 31, v166
	v_lshl_add_u64 v[180:181], v[166:167], 2, s[28:29]
	v_lshl_add_u64 v[166:167], v[196:197], 0, s[6:7]
	v_lshl_add_u64 v[186:187], v[166:167], 2, s[56:57]
	v_lshl_add_u64 v[166:167], v[186:187], 0, v[164:165]
	v_lshl_add_u64 v[168:169], v[186:187], 0, v[168:169]
	v_lshl_add_u64 v[170:171], v[186:187], 0, v[170:171]
	v_lshl_add_u64 v[172:173], v[186:187], 0, v[172:173]
	v_lshl_add_u64 v[174:175], v[186:187], 0, v[174:175]
	v_lshl_add_u64 v[176:177], v[186:187], 0, v[176:177]
	v_lshl_add_u64 v[178:179], v[186:187], 0, v[178:179]
	v_lshl_add_u64 v[182:183], v[186:187], 0, v[182:183]
	v_or_b32_e32 v130, 0x90, v130
	v_ashrrev_i32_e32 v131, 31, v130
	v_lshl_add_u64 v[164:165], v[130:131], 2, s[28:29]
	v_readlane_b32 s45, v253, 2
	v_readlane_b32 s46, v253, 3
	v_readlane_b32 s47, v253, 4
	v_readlane_b32 s48, v253, 5
	v_readlane_b32 s49, v253, 6
	global_load_dwordx4 v[128:131], v[128:129], off
	global_load_dwordx4 v[184:187], v[184:185], off
	global_load_dwordx4 v[180:183], v[180:181], off
	global_load_dwordx4 v[164:167], v[164:165], off
	global_load_dwordx4 v[168:171], v[148:149], off
	global_load_dwordx4 v[172:175], v[150:151], off
	global_load_dwordx4 v[176:179], v[152:153], off
	global_load_dwordx4 v[188:191], v[154:155], off
	global_load_dwordx4 v[216:219], v[148:149], off offset:64
	global_load_dwordx4 v[220:223], v[150:151], off offset:64
	global_load_dwordx4 v[228:231], v[152:153], off offset:64
	global_load_dwordx4 v[232:235], v[154:155], off offset:64
	global_load_dwordx4 v[192:195], v[148:149], off offset:512
	global_load_dwordx4 v[204:207], v[150:151], off offset:512
	global_load_dwordx4 v[208:211], v[152:153], off offset:512
	global_load_dwordx4 v[212:215], v[154:155], off offset:512
	global_load_dwordx4 v[236:239], v[148:149], off offset:576
	global_load_dwordx4 v[240:243], v[150:151], off offset:576
	global_load_dwordx4 v[244:247], v[152:153], off offset:576
	global_load_dwordx4 v[248:251], v[154:155], off offset:576
	s_waitcnt vmcnt(12)
	v_pk_fma_f32 v[52:53], v[52:53], v[128:129], v[168:169]
	v_pk_fma_f32 v[54:55], v[54:55], v[130:131], v[170:171]
	v_pk_fma_f32 v[72:73], v[72:73], v[128:129], v[172:173]
	v_pk_fma_f32 v[74:75], v[74:75], v[130:131], v[174:175]
	v_pk_fma_f32 v[80:81], v[80:81], v[128:129], v[176:177]
	v_pk_fma_f32 v[82:83], v[82:83], v[130:131], v[178:179]
	v_pk_fma_f32 v[88:89], v[88:89], v[128:129], v[188:189]
	v_pk_fma_f32 v[90:91], v[90:91], v[130:131], v[190:191]
	global_store_dwordx4 v[146:147], v[52:55], off
	global_store_dwordx4 v[144:145], v[72:75], off
	global_store_dwordx4 v[142:143], v[80:83], off
	global_store_dwordx4 v[140:141], v[88:91], off
	s_waitcnt vmcnt(12)
	v_pk_fma_f32 v[104:105], v[104:105], v[184:185], v[216:217]
	v_pk_fma_f32 v[106:107], v[106:107], v[186:187], v[218:219]
	v_pk_fma_f32 v[116:117], v[116:117], v[184:185], v[220:221]
	v_pk_fma_f32 v[118:119], v[118:119], v[186:187], v[222:223]
	v_pk_fma_f32 v[108:109], v[108:109], v[184:185], v[228:229]
	v_pk_fma_f32 v[110:111], v[110:111], v[186:187], v[230:231]
	v_pk_fma_f32 v[96:97], v[96:97], v[184:185], v[232:233]
	v_pk_fma_f32 v[98:99], v[98:99], v[186:187], v[234:235]
	global_store_dwordx4 v[146:147], v[104:107], off offset:64
	global_store_dwordx4 v[144:145], v[116:119], off offset:64
	global_store_dwordx4 v[142:143], v[108:111], off offset:64
	global_store_dwordx4 v[140:141], v[96:99], off offset:64
	s_waitcnt vmcnt(12)
	v_pk_fma_f32 v[28:29], v[28:29], v[180:181], v[192:193]
	v_pk_fma_f32 v[30:31], v[30:31], v[182:183], v[194:195]
	v_pk_fma_f32 v[36:37], v[36:37], v[180:181], v[204:205]
	v_pk_fma_f32 v[38:39], v[38:39], v[182:183], v[206:207]
	v_pk_fma_f32 v[40:41], v[40:41], v[180:181], v[208:209]
	v_pk_fma_f32 v[42:43], v[42:43], v[182:183], v[210:211]
	v_pk_fma_f32 v[44:45], v[44:45], v[180:181], v[212:213]
	v_pk_fma_f32 v[46:47], v[46:47], v[182:183], v[214:215]
	global_store_dwordx4 v[146:147], v[28:31], off offset:512
	global_store_dwordx4 v[144:145], v[36:39], off offset:512
	global_store_dwordx4 v[142:143], v[40:43], off offset:512
	global_store_dwordx4 v[140:141], v[44:47], off offset:512
	s_waitcnt vmcnt(12)
	v_pk_fma_f32 v[0:1], v[0:1], v[164:165], v[236:237]
	v_pk_fma_f32 v[2:3], v[2:3], v[166:167], v[238:239]
	v_pk_fma_f32 v[4:5], v[4:5], v[164:165], v[240:241]
	v_pk_fma_f32 v[6:7], v[6:7], v[166:167], v[242:243]
	v_pk_fma_f32 v[8:9], v[8:9], v[164:165], v[244:245]
	v_pk_fma_f32 v[10:11], v[10:11], v[166:167], v[246:247]
	v_pk_fma_f32 v[12:13], v[12:13], v[164:165], v[248:249]
	v_pk_fma_f32 v[14:15], v[14:15], v[166:167], v[250:251]
	global_store_dwordx4 v[146:147], v[0:3], off offset:576
	global_store_dwordx4 v[144:145], v[4:7], off offset:576
	global_store_dwordx4 v[142:143], v[8:11], off offset:576
	global_store_dwordx4 v[140:141], v[12:15], off offset:576
	v_readlane_b32 s40, v254, 59
	s_branch .LBB0_213

.LBB0_251:
	s_andn2_b64 vcc, exec, s[6:7]
	s_cbranch_vccnz .Lh1_idle
	s_sub_i32 s6, 0x180, s55
	s_lshl_b32 s6, s6, 1
	s_cmp_le_i32 s6, s42
	s_cbranch_scc1 .Lh1_top
	s_mov_b32 s28, -1
	s_ashr_i32 s6, s33, 31
	v_mbcnt_lo_u32_b32 v0, s28, 0
	v_mbcnt_hi_u32_b32 v0, s28, v0
	v_add_u32_e32 v132, s43, v0
	s_lshr_b32 s6, s6, 26
	v_bfe_i32 v4, v132, 27, 1
	v_lshlrev_b32_e32 v2, 4, v132
	v_lshrrev_b32_e32 v4, 22, v4
	v_add_u32_e32 v4, v2, v4
	v_and_b32_e32 v4, 0xfffffc00, v4
	v_ashrrev_i32_e32 v3, 31, v132
	v_sub_u32_e32 v4, v2, v4
	v_lshrrev_b32_e32 v3, 26, v3
	v_lshrrev_b32_e32 v5, 4, v4
	v_add_u32_e32 v3, v132, v3
	v_bitop3_b32 v5, v5, v4, 32 bitop3:0x6c
	v_ashrrev_i32_e32 v4, 31, v4
	v_ashrrev_i32_e32 v3, 6, v3
	v_lshrrev_b32_e32 v4, 26, v4
	v_lshlrev_b32_e32 v6, 3, v3
	v_add_u32_e32 v4, v5, v4
	v_and_b32_e32 v6, 0xffff0, v6
	v_ashrrev_i32_e32 v4, 6, v4
	v_add_u32_e32 v6, v4, v6
	v_mul_i32_i24_e32 v4, 64, v4
	v_lshlrev_b32_e32 v3, 5, v3
	v_sub_u32_e32 v4, v5, v4
	v_and_b32_e32 v3, 32, v3
	v_ashrrev_i16_sdwa v4, v226, sext(v4) dst_sel:DWORD dst_unused:UNUSED_PAD src0_sel:DWORD src1_sel:BYTE_0
	v_bfe_i32 v4, v4, 0, 16
	v_lshl_or_b32 v3, v6, 11, v3
	v_add_u32_e32 v2, 0x2000, v2
	v_add_lshl_u32 v128, v3, v4, 1
	v_ashrrev_i32_e32 v3, 31, v2
	s_add_i32 s6, s33, s6
	v_lshrrev_b32_e32 v3, 22, v3
	s_ashr_i32 s7, s6, 6
	s_and_b32 s6, s6, 0xffc0
	v_add_u32_e32 v3, v2, v3
	s_sub_i32 s6, s33, s6
	v_ashrrev_i32_e32 v3, 10, v3
	s_lshl_b32 s52, s7, 3
	s_bfe_i32 s7, s6, 0x80000
	v_mul_i32_i24_e32 v4, 0x400, v3
	s_bfe_u32 s7, s7, 0x3000c
	v_sub_u32_e32 v2, v2, v4
	s_add_i32 s7, s6, s7
	v_lshrrev_b32_e32 v4, 4, v2
	s_bfe_i32 s8, s7, 0x80000
	s_and_b32 s7, s7, 0xf8
	v_bitop3_b32 v2, v4, v2, 32 bitop3:0x6c
	s_sub_i32 s6, s6, s7
	v_ashrrev_i32_e32 v5, 31, v2
	s_sext_i32_i16 s8, s8
	s_sext_i32_i8 s6, s6
	v_lshrrev_b32_e32 v5, 26, v5
	s_add_i32 s52, s52, s6
	s_lshl_b32 s6, s8, 5
	v_add_u32_e32 v5, v2, v5
	s_lshl_b32 s10, s52, 8
	s_and_b32 s6, s6, 0xffffff00
	v_ashrrev_i32_e32 v1, 6, v132
	v_lshlrev_b32_e32 v4, 3, v3
	v_lshrrev_b32_e32 v6, 6, v5
	v_and_b32_e32 v5, 0xc0, v5
	s_ashr_i32 s7, s6, 31
	s_or_b32 s8, s6, 0x80
	s_or_b32 s58, s10, 0x80
	v_readfirstlane_b32 s28, v1
	v_and_b32_e32 v4, 0xffff0, v4
	v_lshlrev_b32_e32 v3, 5, v3
	v_sub_u32_e32 v2, v2, v5
	s_ashr_i32 s11, s10, 31
	s_ashr_i32 s9, s8, 31
	s_ashr_i32 s59, s58, 31
	s_lshl_b32 s53, s28, 10
	v_add_u32_e32 v4, v6, v4
	v_and_b32_e32 v3, 32, v3
	v_ashrrev_i16_sdwa v2, v226, sext(v2) dst_sel:DWORD dst_unused:UNUSED_PAD src0_sel:DWORD src1_sel:BYTE_0
	s_lshl_b64 s[28:29], s[6:7], 12
	v_bfe_i32 v2, v2, 0, 16
	v_lshl_or_b32 v3, v4, 11, v3
	s_add_u32 s64, s34, s28
	v_add_lshl_u32 v130, v3, v2, 1
	s_addc_u32 s65, s54, s29
	s_add_i32 s68, s53, 0x10000
	s_add_i32 s69, s53, 0x12000
	s_lshl_b64 s[56:57], s[10:11], 12
	v_readlane_b32 s33, v254, 14
	v_mov_b32_e32 v2, v128
	v_mov_b32_e32 v3, v130
	s_mov_b32 m0, s68
	s_add_u32 s62, s33, s56
	v_readlane_b32 s38, v254, 15
	s_addc_u32 s63, s38, s57
	global_load_lds_dwordx4 v2, s[64:65]
	s_mov_b32 m0, s69
	s_add_i32 s11, s53, 0x2000
	s_lshl_b64 s[36:37], s[8:9], 12
	global_load_lds_dwordx4 v3, s[64:65]
	v_mov_b32_e32 v2, v128
	v_mov_b32_e32 v3, v130
	s_mov_b32 m0, s53
	s_add_u32 s60, s34, s36
	s_addc_u32 s61, s54, s37
	global_load_lds_dwordx4 v2, s[62:63]
	s_mov_b32 m0, s11
	s_add_i32 s9, s53, 0x14000
	s_add_i32 s70, s53, 0x16000
	s_lshl_b64 s[36:37], s[58:59], 12
	global_load_lds_dwordx4 v3, s[62:63]
	v_mov_b32_e32 v2, v128
	v_mov_b32_e32 v3, v130
	s_mov_b32 m0, s9
	s_add_u32 s58, s33, s36
	s_addc_u32 s59, s38, s37
	global_load_lds_dwordx4 v2, s[60:61]
	s_mov_b32 m0, s70
	s_add_i32 s71, s53, 0x4000
	global_load_lds_dwordx4 v3, s[60:61]
	v_mov_b32_e32 v2, v128
	v_mov_b32_e32 v3, v130
	s_mov_b32 m0, s71
	s_add_i32 s72, s53, 0x6000
	v_ashrrev_i32_e32 v0, 8, v132
	global_load_lds_dwordx4 v2, s[58:59]
	s_mov_b32 m0, s72
	v_cmp_eq_u32_e32 vcc, 1, v0
	global_load_lds_dwordx4 v3, s[58:59]
	s_and_saveexec_b64 s[66:67], vcc
	s_cbranch_execz .LBB0_254
	s_barrier

.LBB0_255:
	ds_read_b128 v[140:143], v129
	ds_read_b128 v[144:147], v129 offset:1024
	ds_read_b128 v[148:151], v129 offset:2048
	ds_read_b128 v[152:155], v129 offset:3072
	s_add_u32 s28, s60, s56
	v_mov_b32_e32 v196, v128
	v_mov_b32_e32 v188, v130
	s_addc_u32 s29, s61, s57
	ds_read_b128 v[156:159], v136
	ds_read_b128 v[160:163], v136 offset:1024
	ds_read_b128 v[164:167], v135
	ds_read_b128 v[168:171], v135 offset:1024
	ds_read_b128 v[172:175], v134
	ds_read_b128 v[176:179], v134 offset:1024
	ds_read_b128 v[180:183], v133
	ds_read_b128 v[184:187], v133 offset:1024
	s_add_i32 s40, s53, 0xc000
	v_lshl_add_u64 v[190:191], s[28:29], 0, v[196:197]
	v_mov_b32_e32 v189, v197
	v_lshl_add_u64 v[190:191], v[190:191], 0, s[44:45]
	s_mov_b32 m0, s40
	v_lshl_add_u64 v[188:189], s[28:29], 0, v[188:189]
	s_add_i32 s39, s53, 0xe000
	global_load_lds_dwordx4 v[190:191], off
	v_lshl_add_u64 v[188:189], v[188:189], 0, s[44:45]
	s_mov_b32 m0, s39
	s_nop 0
	global_load_lds_dwordx4 v[188:189], off
	s_waitcnt lgkmcnt(8)
	s_barrier
	s_waitcnt lgkmcnt(0)
	s_setprio 1
	s_waitcnt lgkmcnt(0)
	v_mfma_f32_16x16x32_bf16 v[124:127], v[140:143], v[156:159], v[124:127]
	v_mfma_f32_16x16x32_bf16 v[120:123], v[148:151], v[156:159], v[120:123]
	v_mfma_f32_16x16x32_bf16 v[116:119], v[140:143], v[164:167], v[116:119]
	v_mfma_f32_16x16x32_bf16 v[112:115], v[148:151], v[164:167], v[112:115]
	v_mfma_f32_16x16x32_bf16 v[108:111], v[140:143], v[172:175], v[108:111]
	v_mfma_f32_16x16x32_bf16 v[104:107], v[148:151], v[172:175], v[104:107]
	v_mfma_f32_16x16x32_bf16 v[100:103], v[140:143], v[180:183], v[100:103]
	v_mfma_f32_16x16x32_bf16 v[96:99], v[148:151], v[180:183], v[96:99]
	v_mfma_f32_16x16x32_bf16 v[124:127], v[144:147], v[160:163], v[124:127]
	v_mfma_f32_16x16x32_bf16 v[120:123], v[152:155], v[160:163], v[120:123]
	v_mfma_f32_16x16x32_bf16 v[116:119], v[144:147], v[168:171], v[116:119]
	v_mfma_f32_16x16x32_bf16 v[112:115], v[152:155], v[168:171], v[112:115]
	v_mfma_f32_16x16x32_bf16 v[108:111], v[144:147], v[176:179], v[108:111]
	v_mfma_f32_16x16x32_bf16 v[104:107], v[152:155], v[176:179], v[104:107]
	v_mfma_f32_16x16x32_bf16 v[100:103], v[144:147], v[184:187], v[100:103]
	v_mfma_f32_16x16x32_bf16 v[96:99], v[152:155], v[184:187], v[96:99]
	s_setprio 0
	s_barrier
	s_add_u32 s62, s60, s36
	v_mov_b32_e32 v196, v128
	v_mov_b32_e32 v210, v130
	s_addc_u32 s63, s61, s37
	ds_read_b128 v[188:191], v139
	ds_read_b128 v[192:195], v139 offset:1024
	ds_read_b128 v[202:205], v139 offset:2048
	ds_read_b128 v[206:209], v139 offset:3072
	v_mov_b32_e32 v211, v197
	v_lshl_add_u64 v[212:213], s[62:63], 0, v[196:197]
	s_mov_b32 m0, s68
	v_lshl_add_u64 v[212:213], v[212:213], 0, s[46:47]
	v_lshl_add_u64 v[210:211], s[62:63], 0, v[210:211]
	global_load_lds_dwordx4 v[212:213], off
	v_lshl_add_u64 v[210:211], v[210:211], 0, s[46:47]
	s_mov_b32 m0, s69
	s_nop 0
	global_load_lds_dwordx4 v[210:211], off
	s_barrier
	s_waitcnt lgkmcnt(0)
	s_setprio 1
	s_waitcnt lgkmcnt(0)
	v_mfma_f32_16x16x32_bf16 v[92:95], v[188:191], v[156:159], v[92:95]
	v_mfma_f32_16x16x32_bf16 v[88:91], v[202:205], v[156:159], v[88:91]
	v_mfma_f32_16x16x32_bf16 v[84:87], v[188:191], v[164:167], v[84:87]
	v_mfma_f32_16x16x32_bf16 v[80:83], v[202:205], v[164:167], v[80:83]
	v_mfma_f32_16x16x32_bf16 v[76:79], v[188:191], v[172:175], v[76:79]
	v_mfma_f32_16x16x32_bf16 v[72:75], v[202:205], v[172:175], v[72:75]
	v_mfma_f32_16x16x32_bf16 v[68:71], v[188:191], v[180:183], v[68:71]
	v_mfma_f32_16x16x32_bf16 v[64:67], v[202:205], v[180:183], v[64:67]
	v_mfma_f32_16x16x32_bf16 v[92:95], v[192:195], v[160:163], v[92:95]
	v_mfma_f32_16x16x32_bf16 v[88:91], v[206:209], v[160:163], v[88:91]
	v_mfma_f32_16x16x32_bf16 v[84:87], v[192:195], v[168:171], v[84:87]
	v_mfma_f32_16x16x32_bf16 v[80:83], v[206:209], v[168:171], v[80:83]
	v_mfma_f32_16x16x32_bf16 v[76:79], v[192:195], v[176:179], v[76:79]
	v_mfma_f32_16x16x32_bf16 v[72:75], v[206:209], v[176:179], v[72:75]
	v_mfma_f32_16x16x32_bf16 v[68:71], v[192:195], v[184:187], v[68:71]
	v_mfma_f32_16x16x32_bf16 v[64:67], v[206:209], v[184:187], v[64:67]
	s_setprio 0
	v_mov_b32_e32 v196, v128
	v_mov_b32_e32 v210, v130
	s_barrier
	ds_read_b128 v[156:159], v136 offset:16384
	ds_read_b128 v[160:163], v136 offset:17408
	ds_read_b128 v[164:167], v135 offset:16384
	ds_read_b128 v[168:171], v135 offset:17408
	ds_read_b128 v[172:175], v134 offset:16384
	ds_read_b128 v[176:179], v134 offset:17408
	ds_read_b128 v[180:183], v133 offset:16384
	ds_read_b128 v[184:187], v133 offset:17408
	v_mov_b32_e32 v211, v197
	v_lshl_add_u64 v[212:213], s[28:29], 0, v[196:197]
	s_mov_b32 m0, s53
	v_lshl_add_u64 v[212:213], v[212:213], 0, s[48:49]
	v_lshl_add_u64 v[210:211], s[28:29], 0, v[210:211]
	global_load_lds_dwordx4 v[212:213], off
	v_lshl_add_u64 v[210:211], v[210:211], 0, s[48:49]
	s_mov_b32 m0, s11
	s_nop 0
	global_load_lds_dwordx4 v[210:211], off
	s_barrier
	s_waitcnt lgkmcnt(0)
	s_setprio 1
	s_waitcnt lgkmcnt(0)
	v_mfma_f32_16x16x32_bf16 v[60:63], v[140:143], v[156:159], v[60:63]
	v_mfma_f32_16x16x32_bf16 v[56:59], v[148:151], v[156:159], v[56:59]
	v_mfma_f32_16x16x32_bf16 v[52:55], v[140:143], v[164:167], v[52:55]
	v_mfma_f32_16x16x32_bf16 v[48:51], v[148:151], v[164:167], v[48:51]
	v_mfma_f32_16x16x32_bf16 v[44:47], v[140:143], v[172:175], v[44:47]
	v_mfma_f32_16x16x32_bf16 v[40:43], v[148:151], v[172:175], v[40:43]
	v_mfma_f32_16x16x32_bf16 v[36:39], v[140:143], v[180:183], v[36:39]
	v_mfma_f32_16x16x32_bf16 v[32:35], v[148:151], v[180:183], v[32:35]
	v_mfma_f32_16x16x32_bf16 v[60:63], v[144:147], v[160:163], v[60:63]
	v_mfma_f32_16x16x32_bf16 v[56:59], v[152:155], v[160:163], v[56:59]
	v_mfma_f32_16x16x32_bf16 v[52:55], v[144:147], v[168:171], v[52:55]
	v_mfma_f32_16x16x32_bf16 v[48:51], v[152:155], v[168:171], v[48:51]
	v_mfma_f32_16x16x32_bf16 v[44:47], v[144:147], v[176:179], v[44:47]
	v_mfma_f32_16x16x32_bf16 v[40:43], v[152:155], v[176:179], v[40:43]
	v_mfma_f32_16x16x32_bf16 v[36:39], v[144:147], v[184:187], v[36:39]
	v_mfma_f32_16x16x32_bf16 v[32:35], v[152:155], v[184:187], v[32:35]
	s_setprio 0
	s_barrier
	v_mov_b32_e32 v196, v128
	v_mov_b32_e32 v140, v130
	v_mov_b32_e32 v141, v197
	v_lshl_add_u64 v[142:143], s[62:63], 0, v[196:197]
	s_mov_b32 m0, s9
	v_lshl_add_u64 v[142:143], v[142:143], 0, s[50:51]
	v_lshl_add_u64 v[140:141], s[62:63], 0, v[140:141]
	global_load_lds_dwordx4 v[142:143], off
	v_lshl_add_u64 v[140:141], v[140:141], 0, s[50:51]
	s_mov_b32 m0, s70
	s_nop 0
	global_load_lds_dwordx4 v[140:141], off
	s_waitcnt vmcnt(6)
	s_barrier
	s_setprio 1
	v_mfma_f32_16x16x32_bf16 v[28:31], v[188:191], v[156:159], v[28:31]
	v_mfma_f32_16x16x32_bf16 v[24:27], v[202:205], v[156:159], v[24:27]
	v_mfma_f32_16x16x32_bf16 v[20:23], v[188:191], v[164:167], v[20:23]
	v_mfma_f32_16x16x32_bf16 v[16:19], v[202:205], v[164:167], v[16:19]
	v_mfma_f32_16x16x32_bf16 v[12:15], v[188:191], v[172:175], v[12:15]
	v_mfma_f32_16x16x32_bf16 v[8:11], v[202:205], v[172:175], v[8:11]
	v_mfma_f32_16x16x32_bf16 v[4:7], v[188:191], v[180:183], v[4:7]
	v_mfma_f32_16x16x32_bf16 v[0:3], v[202:205], v[180:183], v[0:3]
	v_mfma_f32_16x16x32_bf16 v[28:31], v[192:195], v[160:163], v[28:31]
	v_mfma_f32_16x16x32_bf16 v[24:27], v[206:209], v[160:163], v[24:27]
	v_mfma_f32_16x16x32_bf16 v[20:23], v[192:195], v[168:171], v[20:23]
	v_mfma_f32_16x16x32_bf16 v[16:19], v[206:209], v[168:171], v[16:19]
	v_mfma_f32_16x16x32_bf16 v[12:15], v[192:195], v[176:179], v[12:15]
	v_mfma_f32_16x16x32_bf16 v[8:11], v[206:209], v[176:179], v[8:11]
	v_mfma_f32_16x16x32_bf16 v[4:7], v[192:195], v[184:187], v[4:7]
	v_mfma_f32_16x16x32_bf16 v[0:3], v[206:209], v[184:187], v[0:3]
	s_setprio 0
	s_barrier
	ds_read_b128 v[140:143], v138
	ds_read_b128 v[144:147], v138 offset:1024
	ds_read_b128 v[148:151], v138 offset:2048
	ds_read_b128 v[152:155], v138 offset:3072
	v_mov_b32_e32 v196, v128
	v_mov_b32_e32 v188, v130
	ds_read_b128 v[156:159], v136 offset:32768
	ds_read_b128 v[160:163], v136 offset:33792
	ds_read_b128 v[164:167], v135 offset:32768
	ds_read_b128 v[168:171], v135 offset:33792
	ds_read_b128 v[172:175], v134 offset:32768
	ds_read_b128 v[176:179], v134 offset:33792
	ds_read_b128 v[180:183], v133 offset:32768
	ds_read_b128 v[184:187], v133 offset:33792
	v_mov_b32_e32 v189, v197
	v_lshl_add_u64 v[190:191], s[28:29], 0, v[196:197]
	s_mov_b32 m0, s71
	v_lshl_add_u64 v[190:191], v[190:191], 0, s[74:75]
	v_lshl_add_u64 v[188:189], s[28:29], 0, v[188:189]
	global_load_lds_dwordx4 v[190:191], off
	v_lshl_add_u64 v[188:189], v[188:189], 0, s[74:75]
	s_mov_b32 m0, s72
	s_nop 0
	global_load_lds_dwordx4 v[188:189], off
	s_waitcnt lgkmcnt(8)
	s_barrier
	s_waitcnt lgkmcnt(0)
	s_setprio 1
	s_waitcnt lgkmcnt(0)
	v_mfma_f32_16x16x32_bf16 v[124:127], v[140:143], v[156:159], v[124:127]
	v_mfma_f32_16x16x32_bf16 v[120:123], v[148:151], v[156:159], v[120:123]
	v_mfma_f32_16x16x32_bf16 v[116:119], v[140:143], v[164:167], v[116:119]
	v_mfma_f32_16x16x32_bf16 v[112:115], v[148:151], v[164:167], v[112:115]
	v_mfma_f32_16x16x32_bf16 v[108:111], v[140:143], v[172:175], v[108:111]
	v_mfma_f32_16x16x32_bf16 v[104:107], v[148:151], v[172:175], v[104:107]
	v_mfma_f32_16x16x32_bf16 v[100:103], v[140:143], v[180:183], v[100:103]
	v_mfma_f32_16x16x32_bf16 v[96:99], v[148:151], v[180:183], v[96:99]
	v_mfma_f32_16x16x32_bf16 v[124:127], v[144:147], v[160:163], v[124:127]
	v_mfma_f32_16x16x32_bf16 v[120:123], v[152:155], v[160:163], v[120:123]
	v_mfma_f32_16x16x32_bf16 v[116:119], v[144:147], v[168:171], v[116:119]
	v_mfma_f32_16x16x32_bf16 v[112:115], v[152:155], v[168:171], v[112:115]
	v_mfma_f32_16x16x32_bf16 v[108:111], v[144:147], v[176:179], v[108:111]
	v_mfma_f32_16x16x32_bf16 v[104:107], v[152:155], v[176:179], v[104:107]
	v_mfma_f32_16x16x32_bf16 v[100:103], v[144:147], v[184:187], v[100:103]
	v_mfma_f32_16x16x32_bf16 v[96:99], v[152:155], v[184:187], v[96:99]
	s_setprio 0
	s_barrier
	v_mov_b32_e32 v196, v128
	v_mov_b32_e32 v210, v130
	ds_read_b128 v[188:191], v137
	ds_read_b128 v[192:195], v137 offset:1024
	ds_read_b128 v[202:205], v137 offset:2048
	ds_read_b128 v[206:209], v137 offset:3072
	v_mov_b32_e32 v211, v197
	v_lshl_add_u64 v[212:213], s[62:63], 0, v[196:197]
	s_mov_b32 m0, s66
	v_lshl_add_u64 v[212:213], v[212:213], 0, s[90:91]
	v_lshl_add_u64 v[210:211], s[62:63], 0, v[210:211]
	global_load_lds_dwordx4 v[212:213], off
	v_lshl_add_u64 v[210:211], v[210:211], 0, s[90:91]
	s_mov_b32 m0, s64
	s_nop 0
	global_load_lds_dwordx4 v[210:211], off
	s_barrier
	s_waitcnt lgkmcnt(0)
	s_setprio 1
	s_waitcnt lgkmcnt(0)
	v_mfma_f32_16x16x32_bf16 v[92:95], v[188:191], v[156:159], v[92:95]
	v_mfma_f32_16x16x32_bf16 v[88:91], v[202:205], v[156:159], v[88:91]
	v_mfma_f32_16x16x32_bf16 v[84:87], v[188:191], v[164:167], v[84:87]
	v_mfma_f32_16x16x32_bf16 v[80:83], v[202:205], v[164:167], v[80:83]
	v_mfma_f32_16x16x32_bf16 v[76:79], v[188:191], v[172:175], v[76:79]
	v_mfma_f32_16x16x32_bf16 v[72:75], v[202:205], v[172:175], v[72:75]
	v_mfma_f32_16x16x32_bf16 v[68:71], v[188:191], v[180:183], v[68:71]
	v_mfma_f32_16x16x32_bf16 v[64:67], v[202:205], v[180:183], v[64:67]
	v_mfma_f32_16x16x32_bf16 v[92:95], v[192:195], v[160:163], v[92:95]
	v_mfma_f32_16x16x32_bf16 v[88:91], v[206:209], v[160:163], v[88:91]
	v_mfma_f32_16x16x32_bf16 v[84:87], v[192:195], v[168:171], v[84:87]
	v_mfma_f32_16x16x32_bf16 v[80:83], v[206:209], v[168:171], v[80:83]
	v_mfma_f32_16x16x32_bf16 v[76:79], v[192:195], v[176:179], v[76:79]
	v_mfma_f32_16x16x32_bf16 v[72:75], v[206:209], v[176:179], v[72:75]
	v_mfma_f32_16x16x32_bf16 v[68:71], v[192:195], v[184:187], v[68:71]
	v_mfma_f32_16x16x32_bf16 v[64:67], v[206:209], v[184:187], v[64:67]
	s_setprio 0
	v_mov_b32_e32 v196, v128
	v_mov_b32_e32 v210, v130
	s_barrier
	ds_read_b128 v[156:159], v136 offset:49152
	ds_read_b128 v[160:163], v136 offset:50176
	ds_read_b128 v[164:167], v135 offset:49152
	ds_read_b128 v[168:171], v135 offset:50176
	ds_read_b128 v[172:175], v134 offset:49152
	ds_read_b128 v[176:179], v134 offset:50176
	ds_read_b128 v[180:183], v133 offset:49152
	ds_read_b128 v[184:187], v133 offset:50176
	v_mov_b32_e32 v211, v197
	v_lshl_add_u64 v[212:213], s[28:29], 0, v[196:197]
	s_mov_b32 m0, s65
	v_lshl_add_u64 v[212:213], v[212:213], 0, s[92:93]
	v_lshl_add_u64 v[210:211], s[28:29], 0, v[210:211]
	global_load_lds_dwordx4 v[212:213], off
	v_lshl_add_u64 v[210:211], v[210:211], 0, s[92:93]
	s_mov_b32 m0, s67
	s_nop 0
	global_load_lds_dwordx4 v[210:211], off
	s_barrier
	s_waitcnt lgkmcnt(0)
	s_setprio 1
	s_waitcnt lgkmcnt(0)
	v_mfma_f32_16x16x32_bf16 v[60:63], v[140:143], v[156:159], v[60:63]
	v_mfma_f32_16x16x32_bf16 v[56:59], v[148:151], v[156:159], v[56:59]
	v_mfma_f32_16x16x32_bf16 v[52:55], v[140:143], v[164:167], v[52:55]
	v_mfma_f32_16x16x32_bf16 v[48:51], v[148:151], v[164:167], v[48:51]
	v_mfma_f32_16x16x32_bf16 v[44:47], v[140:143], v[172:175], v[44:47]
	v_mfma_f32_16x16x32_bf16 v[40:43], v[148:151], v[172:175], v[40:43]
	v_mfma_f32_16x16x32_bf16 v[36:39], v[140:143], v[180:183], v[36:39]
	v_mfma_f32_16x16x32_bf16 v[32:35], v[148:151], v[180:183], v[32:35]
	v_mfma_f32_16x16x32_bf16 v[60:63], v[144:147], v[160:163], v[60:63]
	v_mfma_f32_16x16x32_bf16 v[56:59], v[152:155], v[160:163], v[56:59]
	v_mfma_f32_16x16x32_bf16 v[52:55], v[144:147], v[168:171], v[52:55]
	v_mfma_f32_16x16x32_bf16 v[48:51], v[152:155], v[168:171], v[48:51]
	v_mfma_f32_16x16x32_bf16 v[44:47], v[144:147], v[176:179], v[44:47]
	v_mfma_f32_16x16x32_bf16 v[40:43], v[152:155], v[176:179], v[40:43]
	v_mfma_f32_16x16x32_bf16 v[36:39], v[144:147], v[184:187], v[36:39]
	v_mfma_f32_16x16x32_bf16 v[32:35], v[152:155], v[184:187], v[32:35]
	s_setprio 0
	s_barrier
	v_mov_b32_e32 v196, v128
	v_mov_b32_e32 v140, v130
	v_mov_b32_e32 v141, v197
	v_lshl_add_u64 v[142:143], s[62:63], 0, v[196:197]
	s_mov_b32 m0, s33
	v_lshl_add_u64 v[142:143], v[142:143], 0, s[96:97]
	v_lshl_add_u64 v[140:141], s[62:63], 0, v[140:141]
	global_load_lds_dwordx4 v[142:143], off
	v_lshl_add_u64 v[140:141], v[140:141], 0, s[96:97]
	s_mov_b32 m0, s73
	s_nop 0
	global_load_lds_dwordx4 v[140:141], off
	s_waitcnt vmcnt(6)
	s_barrier
	s_setprio 1
	v_mfma_f32_16x16x32_bf16 v[28:31], v[188:191], v[156:159], v[28:31]
	v_mfma_f32_16x16x32_bf16 v[24:27], v[202:205], v[156:159], v[24:27]
	v_mfma_f32_16x16x32_bf16 v[20:23], v[188:191], v[164:167], v[20:23]
	v_mfma_f32_16x16x32_bf16 v[16:19], v[202:205], v[164:167], v[16:19]
	v_mfma_f32_16x16x32_bf16 v[12:15], v[188:191], v[172:175], v[12:15]
	v_mfma_f32_16x16x32_bf16 v[8:11], v[202:205], v[172:175], v[8:11]
	v_mfma_f32_16x16x32_bf16 v[4:7], v[188:191], v[180:183], v[4:7]
	v_mfma_f32_16x16x32_bf16 v[0:3], v[202:205], v[180:183], v[0:3]
	v_mfma_f32_16x16x32_bf16 v[28:31], v[192:195], v[160:163], v[28:31]
	v_mfma_f32_16x16x32_bf16 v[24:27], v[206:209], v[160:163], v[24:27]
	v_mfma_f32_16x16x32_bf16 v[20:23], v[192:195], v[168:171], v[20:23]
	v_mfma_f32_16x16x32_bf16 v[16:19], v[206:209], v[168:171], v[16:19]
	v_mfma_f32_16x16x32_bf16 v[12:15], v[192:195], v[176:179], v[12:15]
	v_mfma_f32_16x16x32_bf16 v[8:11], v[206:209], v[176:179], v[8:11]
	v_mfma_f32_16x16x32_bf16 v[4:7], v[192:195], v[184:187], v[4:7]
	v_mfma_f32_16x16x32_bf16 v[0:3], v[206:209], v[184:187], v[0:3]
	s_setprio 0
	s_add_i32 s38, s38, 2
	s_add_u32 s60, s60, 0x100
	s_addc_u32 s61, s61, 0
	s_cmp_lt_u32 s38, 28
	s_barrier
	s_cbranch_scc1 .LBB0_255
	ds_read_b128 v[140:143], v129
	ds_read_b128 v[144:147], v129 offset:1024
	ds_read_b128 v[148:151], v129 offset:2048
	ds_read_b128 v[152:155], v129 offset:3072
	ds_read_b128 v[156:159], v136
	ds_read_b128 v[160:163], v136 offset:1024
	ds_read_b128 v[164:167], v135
	ds_read_b128 v[168:171], v135 offset:1024
	ds_read_b128 v[172:175], v134
	ds_read_b128 v[176:179], v134 offset:1024
	ds_read_b128 v[180:183], v133
	ds_read_b128 v[184:187], v133 offset:1024
	v_mov_b32_e32 v129, v197
	v_lshl_add_u64 v[128:129], s[58:59], 0, v[128:129]
	s_mov_b64 s[28:29], 0xf80
	s_mov_b32 m0, s40
	v_lshl_add_u64 v[128:129], v[128:129], 0, s[28:29]
	v_mov_b32_e32 v131, v197
	global_load_lds_dwordx4 v[128:129], off
	v_lshl_add_u64 v[128:129], s[58:59], 0, v[130:131]
	v_lshl_add_u64 v[128:129], v[128:129], 0, s[28:29]
	s_mov_b32 m0, s39
	s_nop 0
	global_load_lds_dwordx4 v[128:129], off
	s_barrier
	s_waitcnt lgkmcnt(0)
	s_setprio 1
	s_waitcnt lgkmcnt(0)
	v_mfma_f32_16x16x32_bf16 v[124:127], v[140:143], v[156:159], v[124:127]
	v_mfma_f32_16x16x32_bf16 v[120:123], v[148:151], v[156:159], v[120:123]
	v_mfma_f32_16x16x32_bf16 v[116:119], v[140:143], v[164:167], v[116:119]
	v_mfma_f32_16x16x32_bf16 v[112:115], v[148:151], v[164:167], v[112:115]
	v_mfma_f32_16x16x32_bf16 v[108:111], v[140:143], v[172:175], v[108:111]
	v_mfma_f32_16x16x32_bf16 v[100:103], v[140:143], v[180:183], v[100:103]
	v_mfma_f32_16x16x32_bf16 v[96:99], v[148:151], v[180:183], v[96:99]
	v_mfma_f32_16x16x32_bf16 v[124:127], v[144:147], v[160:163], v[124:127]
	v_mfma_f32_16x16x32_bf16 v[120:123], v[152:155], v[160:163], v[120:123]
	v_mfma_f32_16x16x32_bf16 v[116:119], v[144:147], v[168:171], v[116:119]
	v_mfma_f32_16x16x32_bf16 v[112:115], v[152:155], v[168:171], v[112:115]
	v_mfma_f32_16x16x32_bf16 v[108:111], v[144:147], v[176:179], v[108:111]
	v_mfma_f32_16x16x32_bf16 v[104:107], v[148:151], v[172:175], v[104:107]
	v_mfma_f32_16x16x32_bf16 v[100:103], v[144:147], v[184:187], v[100:103]
	v_mfma_f32_16x16x32_bf16 v[96:99], v[152:155], v[184:187], v[96:99]
	v_mfma_f32_16x16x32_bf16 v[128:131], v[152:155], v[176:179], v[104:107]
	s_setprio 0
	s_barrier
	s_nop 2
	ds_read_b128 v[104:107], v139
	ds_read_b128 v[188:191], v139 offset:1024
	ds_read_b128 v[192:195], v139 offset:2048
	ds_read_b128 v[202:205], v139 offset:3072
	s_barrier
	s_waitcnt lgkmcnt(0)
	s_setprio 1
	s_waitcnt lgkmcnt(0)
	v_mfma_f32_16x16x32_bf16 v[92:95], v[104:107], v[156:159], v[92:95]
	v_mfma_f32_16x16x32_bf16 v[84:87], v[104:107], v[164:167], v[84:87]
	v_mfma_f32_16x16x32_bf16 v[76:79], v[104:107], v[172:175], v[76:79]
	v_mfma_f32_16x16x32_bf16 v[68:71], v[104:107], v[180:183], v[68:71]
	v_mfma_f32_16x16x32_bf16 v[64:67], v[192:195], v[180:183], v[64:67]
	v_mfma_f32_16x16x32_bf16 v[92:95], v[188:191], v[160:163], v[92:95]
	v_mfma_f32_16x16x32_bf16 v[88:91], v[192:195], v[156:159], v[88:91]
	v_mfma_f32_16x16x32_bf16 v[84:87], v[188:191], v[168:171], v[84:87]
	v_mfma_f32_16x16x32_bf16 v[80:83], v[192:195], v[164:167], v[80:83]
	v_mfma_f32_16x16x32_bf16 v[76:79], v[188:191], v[176:179], v[76:79]
	v_mfma_f32_16x16x32_bf16 v[72:75], v[192:195], v[172:175], v[72:75]
	v_mfma_f32_16x16x32_bf16 v[68:71], v[188:191], v[184:187], v[68:71]
	v_mfma_f32_16x16x32_bf16 v[64:67], v[202:205], v[184:187], v[64:67]
	v_mfma_f32_16x16x32_bf16 v[156:159], v[202:205], v[160:163], v[88:91]
	v_mfma_f32_16x16x32_bf16 v[160:163], v[202:205], v[168:171], v[80:83]
	v_mfma_f32_16x16x32_bf16 v[164:167], v[202:205], v[176:179], v[72:75]
	s_setprio 0
	s_barrier
	s_nop 0
	ds_read_b128 v[72:75], v136 offset:16384
	ds_read_b128 v[80:83], v136 offset:17408
	ds_read_b128 v[88:91], v135 offset:16384
	ds_read_b128 v[168:171], v135 offset:17408
	ds_read_b128 v[172:175], v134 offset:16384
	ds_read_b128 v[176:179], v134 offset:17408
	ds_read_b128 v[180:183], v133 offset:16384
	ds_read_b128 v[184:187], v133 offset:17408
	s_waitcnt vmcnt(4)
	s_barrier
	s_waitcnt lgkmcnt(0)
	s_setprio 1
	s_waitcnt lgkmcnt(0)
	v_mfma_f32_16x16x32_bf16 v[60:63], v[140:143], v[72:75], v[60:63]
	v_mfma_f32_16x16x32_bf16 v[56:59], v[148:151], v[72:75], v[56:59]
	v_mfma_f32_16x16x32_bf16 v[48:51], v[148:151], v[88:91], v[48:51]
	v_mfma_f32_16x16x32_bf16 v[32:35], v[148:151], v[180:183], v[32:35]
	v_mfma_f32_16x16x32_bf16 v[60:63], v[144:147], v[80:83], v[60:63]
	v_mfma_f32_16x16x32_bf16 v[56:59], v[152:155], v[80:83], v[56:59]
	v_mfma_f32_16x16x32_bf16 v[52:55], v[140:143], v[88:91], v[52:55]
	v_mfma_f32_16x16x32_bf16 v[48:51], v[152:155], v[168:171], v[48:51]
	v_mfma_f32_16x16x32_bf16 v[44:47], v[140:143], v[172:175], v[44:47]
	v_mfma_f32_16x16x32_bf16 v[40:43], v[148:151], v[172:175], v[40:43]
	v_mfma_f32_16x16x32_bf16 v[36:39], v[140:143], v[180:183], v[36:39]
	v_mfma_f32_16x16x32_bf16 v[32:35], v[152:155], v[184:187], v[32:35]
	v_mfma_f32_16x16x32_bf16 v[206:209], v[144:147], v[168:171], v[52:55]
	v_mfma_f32_16x16x32_bf16 v[210:213], v[144:147], v[176:179], v[44:47]
	v_mfma_f32_16x16x32_bf16 v[214:217], v[152:155], v[176:179], v[40:43]
	v_mfma_f32_16x16x32_bf16 v[140:143], v[144:147], v[184:187], v[36:39]
	s_setprio 0
	s_setprio 1
	v_mfma_f32_16x16x32_bf16 v[24:27], v[192:195], v[72:75], v[24:27]
	v_mfma_f32_16x16x32_bf16 v[20:23], v[104:107], v[88:91], v[20:23]
	v_mfma_f32_16x16x32_bf16 v[28:31], v[104:107], v[72:75], v[28:31]
	v_mfma_f32_16x16x32_bf16 v[24:27], v[202:205], v[80:83], v[24:27]
	v_mfma_f32_16x16x32_bf16 v[20:23], v[188:191], v[168:171], v[20:23]
	v_mfma_f32_16x16x32_bf16 v[16:19], v[192:195], v[88:91], v[16:19]
	v_mfma_f32_16x16x32_bf16 v[12:15], v[104:107], v[172:175], v[12:15]
	v_mfma_f32_16x16x32_bf16 v[8:11], v[192:195], v[172:175], v[8:11]
	v_mfma_f32_16x16x32_bf16 v[4:7], v[104:107], v[180:183], v[4:7]
	v_mfma_f32_16x16x32_bf16 v[0:3], v[192:195], v[180:183], v[0:3]
	v_mfma_f32_16x16x32_bf16 v[144:147], v[188:191], v[80:83], v[28:31]
	v_mfma_f32_16x16x32_bf16 v[148:151], v[202:205], v[168:171], v[16:19]
	v_mfma_f32_16x16x32_bf16 v[152:155], v[188:191], v[176:179], v[12:15]
	v_mfma_f32_16x16x32_bf16 v[168:171], v[202:205], v[176:179], v[8:11]
	v_mfma_f32_16x16x32_bf16 v[172:175], v[188:191], v[184:187], v[4:7]
	v_mfma_f32_16x16x32_bf16 v[176:179], v[202:205], v[184:187], v[0:3]
	s_setprio 0
	s_barrier
	ds_read_b128 v[16:19], v138
	ds_read_b128 v[180:183], v138 offset:1024
	ds_read_b128 v[184:187], v138 offset:2048
	ds_read_b128 v[188:191], v138 offset:3072
	ds_read_b128 v[0:3], v136 offset:32768
	ds_read_b128 v[4:7], v136 offset:33792
	ds_read_b128 v[8:11], v135 offset:32768
	ds_read_b128 v[12:15], v135 offset:33792
	ds_read_b128 v[44:47], v134 offset:32768
	ds_read_b128 v[192:195], v134 offset:33792
	ds_read_b128 v[202:205], v133 offset:32768
	ds_read_b128 v[218:221], v133 offset:33792
	s_waitcnt vmcnt(2)
	s_barrier
	s_waitcnt lgkmcnt(0)
	s_setprio 1
	s_waitcnt lgkmcnt(0)
	v_mfma_f32_16x16x32_bf16 v[28:31], v[16:19], v[0:3], v[124:127]
	v_mfma_f32_16x16x32_bf16 v[52:55], v[180:183], v[4:7], v[28:31]
	v_mfma_f32_16x16x32_bf16 v[28:31], v[184:187], v[0:3], v[120:123]
	v_mfma_f32_16x16x32_bf16 v[104:107], v[188:191], v[4:7], v[28:31]
	v_mfma_f32_16x16x32_bf16 v[28:31], v[16:19], v[8:11], v[116:119]
	v_mfma_f32_16x16x32_bf16 v[72:75], v[180:183], v[12:15], v[28:31]
	v_mfma_f32_16x16x32_bf16 v[28:31], v[184:187], v[8:11], v[112:115]
	v_mfma_f32_16x16x32_bf16 v[116:119], v[188:191], v[12:15], v[28:31]
	v_mfma_f32_16x16x32_bf16 v[28:31], v[16:19], v[44:47], v[108:111]
	v_mfma_f32_16x16x32_bf16 v[80:83], v[180:183], v[192:195], v[28:31]
	v_mfma_f32_16x16x32_bf16 v[28:31], v[184:187], v[44:47], v[128:131]
	v_mfma_f32_16x16x32_bf16 v[108:111], v[188:191], v[192:195], v[28:31]
	v_mfma_f32_16x16x32_bf16 v[28:31], v[16:19], v[202:205], v[100:103]
	v_mfma_f32_16x16x32_bf16 v[88:91], v[180:183], v[218:221], v[28:31]
	v_mfma_f32_16x16x32_bf16 v[28:31], v[184:187], v[202:205], v[96:99]
	v_mfma_f32_16x16x32_bf16 v[96:99], v[188:191], v[218:221], v[28:31]
	s_setprio 0
	s_barrier
	ds_read_b128 v[128:131], v137
	ds_read_b128 v[222:225], v137 offset:1024
	ds_read_b128 v[228:231], v137 offset:2048
	ds_read_b128 v[232:235], v137 offset:3072
	s_waitcnt vmcnt(0)
	s_barrier
	s_waitcnt lgkmcnt(0)
	s_setprio 1
	s_waitcnt lgkmcnt(0)
	v_mfma_f32_16x16x32_bf16 v[28:31], v[128:131], v[0:3], v[92:95]
	v_mfma_f32_16x16x32_bf16 v[0:3], v[228:231], v[0:3], v[156:159]
	v_mfma_f32_16x16x32_bf16 v[28:31], v[222:225], v[4:7], v[28:31]
	v_mfma_f32_16x16x32_bf16 v[0:3], v[232:235], v[4:7], v[0:3]
	v_mfma_f32_16x16x32_bf16 v[4:7], v[128:131], v[8:11], v[84:87]
	v_mfma_f32_16x16x32_bf16 v[36:39], v[222:225], v[12:15], v[4:7]
	v_mfma_f32_16x16x32_bf16 v[4:7], v[228:231], v[8:11], v[160:163]
	v_mfma_f32_16x16x32_bf16 v[4:7], v[232:235], v[12:15], v[4:7]
	v_mfma_f32_16x16x32_bf16 v[8:11], v[128:131], v[44:47], v[76:79]
	v_mfma_f32_16x16x32_bf16 v[12:15], v[128:131], v[202:205], v[68:71]
	v_mfma_f32_16x16x32_bf16 v[40:43], v[222:225], v[192:195], v[8:11]
	v_mfma_f32_16x16x32_bf16 v[8:11], v[228:231], v[44:47], v[164:167]
	v_mfma_f32_16x16x32_bf16 v[44:47], v[222:225], v[218:221], v[12:15]
	v_mfma_f32_16x16x32_bf16 v[12:15], v[228:231], v[202:205], v[64:67]
	v_mfma_f32_16x16x32_bf16 v[8:11], v[232:235], v[192:195], v[8:11]
	v_mfma_f32_16x16x32_bf16 v[12:15], v[232:235], v[218:221], v[12:15]
	s_setprio 0
	s_barrier
	ds_read_b128 v[64:67], v136 offset:49152
	ds_read_b128 v[136:139], v136 offset:50176
	ds_read_b128 v[156:159], v135 offset:49152
	ds_read_b128 v[160:163], v135 offset:50176
	ds_read_b128 v[164:167], v134 offset:49152
	ds_read_b128 v[192:195], v134 offset:50176
	ds_read_b128 v[202:205], v133 offset:49152
	ds_read_b128 v[218:221], v133 offset:50176
	s_barrier
	s_waitcnt lgkmcnt(0)
	s_setprio 1
	s_waitcnt lgkmcnt(0)
	v_mfma_f32_16x16x32_bf16 v[56:59], v[184:187], v[64:67], v[56:59]
	v_mfma_f32_16x16x32_bf16 v[48:51], v[184:187], v[156:159], v[48:51]
	v_mfma_f32_16x16x32_bf16 v[60:63], v[16:19], v[64:67], v[60:63]
	v_mfma_f32_16x16x32_bf16 v[92:95], v[188:191], v[136:139], v[56:59]
	v_mfma_f32_16x16x32_bf16 v[56:59], v[16:19], v[156:159], v[206:209]
	v_mfma_f32_16x16x32_bf16 v[84:87], v[188:191], v[160:163], v[48:51]
	v_mfma_f32_16x16x32_bf16 v[48:51], v[16:19], v[164:167], v[210:213]
	v_mfma_f32_16x16x32_bf16 v[16:19], v[16:19], v[202:205], v[140:143]
	v_mfma_f32_16x16x32_bf16 v[120:123], v[180:183], v[192:195], v[48:51]
	v_mfma_f32_16x16x32_bf16 v[48:51], v[184:187], v[164:167], v[214:217]
	v_mfma_f32_16x16x32_bf16 v[124:127], v[180:183], v[218:221], v[16:19]
	v_mfma_f32_16x16x32_bf16 v[16:19], v[184:187], v[202:205], v[32:35]
	v_mfma_f32_16x16x32_bf16 v[100:103], v[180:183], v[136:139], v[60:63]
	v_mfma_f32_16x16x32_bf16 v[112:115], v[180:183], v[160:163], v[56:59]
	v_mfma_f32_16x16x32_bf16 v[76:79], v[188:191], v[192:195], v[48:51]
	v_mfma_f32_16x16x32_bf16 v[68:71], v[188:191], v[218:221], v[16:19]
	s_setprio 0
	s_setprio 1
	v_mfma_f32_16x16x32_bf16 v[16:19], v[128:131], v[64:67], v[144:147]
	v_mfma_f32_16x16x32_bf16 v[48:51], v[222:225], v[136:139], v[16:19]
	v_mfma_f32_16x16x32_bf16 v[16:19], v[228:231], v[64:67], v[24:27]
	v_mfma_f32_16x16x32_bf16 v[20:23], v[128:131], v[156:159], v[20:23]
	v_mfma_f32_16x16x32_bf16 v[24:27], v[128:131], v[164:167], v[152:155]
	v_mfma_f32_16x16x32_bf16 v[32:35], v[128:131], v[202:205], v[172:175]
	v_mfma_f32_16x16x32_bf16 v[56:59], v[222:225], v[160:163], v[20:23]
	v_mfma_f32_16x16x32_bf16 v[20:23], v[228:231], v[156:159], v[148:151]
	v_mfma_f32_16x16x32_bf16 v[60:63], v[222:225], v[192:195], v[24:27]
	v_mfma_f32_16x16x32_bf16 v[24:27], v[228:231], v[164:167], v[168:171]
	v_mfma_f32_16x16x32_bf16 v[64:67], v[222:225], v[218:221], v[32:35]
	v_mfma_f32_16x16x32_bf16 v[32:35], v[228:231], v[202:205], v[176:179]
	v_mfma_f32_16x16x32_bf16 v[16:19], v[232:235], v[136:139], v[16:19]
	v_mfma_f32_16x16x32_bf16 v[20:23], v[232:235], v[160:163], v[20:23]
	v_mfma_f32_16x16x32_bf16 v[24:27], v[232:235], v[192:195], v[24:27]
	v_mfma_f32_16x16x32_bf16 v[32:35], v[232:235], v[218:221], v[32:35]
	s_setprio 0
	s_movk_i32 s9, 0x100
	v_cmp_gt_u32_e32 vcc, s9, v132
	s_barrier
	s_and_saveexec_b64 s[28:29], vcc
	s_cbranch_execz .LBB0_212
	s_barrier
	s_branch .LBB0_212
.Ltr_925:
	s_branch .LBB0_925
.Ltr_21:
	s_branch .LBB0_21
.LBB0_258:
	v_readlane_b32 s77, v254, 58
